# v33: packed f32 mul/add in FFN-up and gate sigmoid chains; FFN-up store address as 32-bit offset + saddr
# speedup vs baseline: 1.0143x; 1.0029x over previous
; __device__ __forceinline__ float lo2f(unsigned w) { return __uint_as_float(w << 16); }
; __device__ __forceinline__ float hi2f(unsigned w) { return __uint_as_float(w & 0xffff0000u); }
; __device__ __forceinline__ float sigm(float x) { return __builtin_amdgcn_rcpf(1.f + __expf(-x)); }
;   __device__ __forceinline__ void operator()(const f32x4 (&acc)[2][2][4][2], const Unit& u, int wr, int wc, int fr, int fq) const {
;     ...
;       const int q = s - 4, bjq = q >> 1, nq = q & 1;
; #pragma unroll
;       for (int ai = 0; ai < 2; ++ai)
; #pragma unroll
;         for (int m = 0; m < 4; ++m) {
;           float o[4] = {0.f, 0.f, 0.f, 0.f};
; #pragma unroll
;           for (int bj = 0; bj < 2; ++bj)
; #pragma unroll
;             for (int n = 0; n < 2; ++n) {
;               const int ib = 2 * bj + n;
;               const uint2 b2 = *(reinterpret_cast<const uint2*>(brs + (size_t)(ib * 16 + (ai * 2 + bjq) * 4 + m) * 512 + tid) + nq);
;               const f32x4 g = acc[ai][bj][m][n];
;               o[0] += sigm(g[0]) * lo2f(b2.x); o[1] += sigm(g[1]) * hi2f(b2.x);
;               o[2] += sigm(g[2]) * lo2f(b2.y); o[3] += sigm(g[3]) * hi2f(b2.y);
;             }
;           const int r = u.pm * 256 + ai * 128 + wr * 64 + m * 16 + fr;
;           const int d = dq * 256 + 64 * q + 16 * wc + 4 * fq;
;           uint2 w; w.x = pack2(o[0], o[1]); w.y = pack2(o[2], o[3]);
;           *reinterpret_cast<uint2*>(ACC + (size_t)r * 1024 + d) = w;
;         }
.LBB0_1416:
	s_mov_b32 s100, 0xbfb8aa3b
	s_add_i32 s15, s11, -4
	s_and_b32 s19, s2, 1
	s_lshl_b32 s2, s2, 5
	s_and_b32 s2, s2, 0xffffff00
	s_lshl_b32 s18, s15, 1
	s_lshl_b32 s15, s15, 6
	s_add_i32 s15, s15, s2
	s_and_b32 s14, s18, 0x7ffffffc
	s_lshl_b32 s2, s19, 3
	s_lshl_b32 s14, s14, 13
	s_add_i32 s2, s2, s14
	v_lshlrev_b32_e32 v144, 4, v140
	v_add_u32_e32 v144, s2, v144
	v_mov_b32_e32 v170, v144
	global_load_dwordx2 v[146:147], v170, s[48:49]
	v_add_u32_e32 v171, 0x20000, v144
	global_load_dwordx2 v[148:149], v171, s[48:49]
	v_add_u32_e32 v172, 0x40000, v144
	global_load_dwordx2 v[150:151], v172, s[48:49]
	v_add_u32_e32 v173, 0x60000, v144
	global_load_dwordx2 v[152:153], v173, s[48:49]
	v_add_u32_e32 v170, 0x2000, v144
	global_load_dwordx2 v[154:155], v170, s[48:49]
	v_add_u32_e32 v171, 0x22000, v144
	global_load_dwordx2 v[156:157], v171, s[48:49]
	v_add_u32_e32 v172, 0x42000, v144
	global_load_dwordx2 v[158:159], v172, s[48:49]
	v_add_u32_e32 v173, 0x62000, v144
	global_load_dwordx2 v[160:161], v173, s[48:49]
	v_add_u32_e32 v170, 0x4000, v144
	global_load_dwordx2 v[162:163], v170, s[48:49]
	v_add_u32_e32 v171, 0x24000, v144
	global_load_dwordx2 v[164:165], v171, s[48:49]
	v_add_u32_e32 v172, 0x44000, v144
	global_load_dwordx2 v[166:167], v172, s[48:49]
	v_add_u32_e32 v173, 0x64000, v144
	global_load_dwordx2 v[168:169], v173, s[48:49]
	v_or_b32_e32 v145, s15, v200
	v_lshl_add_u32 v143, s16, 8, v1
	v_lshlrev_b32_e32 v145, 1, v145
	v_lshl_add_u32 v145, v143, 11, v145
	v_pk_mul_f32 v[174:175], v[126:127], s[100:101] op_sel_hi:[1,0]
	v_pk_mul_f32 v[182:183], v[128:129], s[100:101] op_sel_hi:[1,0]
	v_exp_f32_e32 v174, v174
	v_exp_f32_e32 v175, v175
	v_exp_f32_e32 v182, v182
	v_exp_f32_e32 v183, v183
	v_pk_add_f32 v[174:175], v[174:175], 1.0 op_sel_hi:[1,0]
	v_pk_add_f32 v[182:183], v[182:183], 1.0 op_sel_hi:[1,0]
	v_rcp_f32_e32 v202, v174
	v_rcp_f32_e32 v203, v175
	v_rcp_f32_e32 v204, v182
	v_rcp_f32_e32 v205, v183
	v_pk_mul_f32 v[174:175], v[122:123], s[100:101] op_sel_hi:[1,0]
	v_pk_mul_f32 v[182:183], v[124:125], s[100:101] op_sel_hi:[1,0]
	v_exp_f32_e32 v174, v174
	v_exp_f32_e32 v175, v175
	v_exp_f32_e32 v182, v182
	v_exp_f32_e32 v183, v183
	v_pk_add_f32 v[174:175], v[174:175], 1.0 op_sel_hi:[1,0]
	v_pk_add_f32 v[182:183], v[182:183], 1.0 op_sel_hi:[1,0]
	v_rcp_f32_e32 v206, v174
	v_rcp_f32_e32 v207, v175
	v_rcp_f32_e32 v208, v182
	v_rcp_f32_e32 v209, v183
	v_pk_mul_f32 v[174:175], v[94:95], s[100:101] op_sel_hi:[1,0]
	v_pk_mul_f32 v[182:183], v[96:97], s[100:101] op_sel_hi:[1,0]
	v_exp_f32_e32 v174, v174
	v_exp_f32_e32 v175, v175
	v_exp_f32_e32 v182, v182
	v_exp_f32_e32 v183, v183
	v_pk_add_f32 v[174:175], v[174:175], 1.0 op_sel_hi:[1,0]
	v_pk_add_f32 v[182:183], v[182:183], 1.0 op_sel_hi:[1,0]
	v_rcp_f32_e32 v210, v174
	v_rcp_f32_e32 v211, v175
	v_rcp_f32_e32 v212, v182
	v_rcp_f32_e32 v213, v183
	v_pk_mul_f32 v[174:175], v[90:91], s[100:101] op_sel_hi:[1,0]
	v_pk_mul_f32 v[182:183], v[92:93], s[100:101] op_sel_hi:[1,0]
	v_exp_f32_e32 v174, v174
	v_exp_f32_e32 v175, v175
	v_exp_f32_e32 v182, v182
	v_exp_f32_e32 v183, v183
	v_pk_add_f32 v[174:175], v[174:175], 1.0 op_sel_hi:[1,0]
	v_pk_add_f32 v[182:183], v[182:183], 1.0 op_sel_hi:[1,0]
	v_rcp_f32_e32 v214, v174
	v_rcp_f32_e32 v215, v175
	v_rcp_f32_e32 v216, v182
	v_rcp_f32_e32 v217, v183
	s_waitcnt vmcnt(8)
	v_lshlrev_b32_e32 v218, 16, v146
	v_and_b32_e32 v219, 0xffff0000, v146
	v_lshlrev_b32_e32 v220, 16, v147
	v_and_b32_e32 v221, 0xffff0000, v147
	v_pk_fma_f32 v[222:223], v[202:203], v[218:219], 0 op_sel_hi:[1,1,0]
	v_pk_fma_f32 v[224:225], v[204:205], v[220:221], 0 op_sel_hi:[1,1,0]
	v_lshlrev_b32_e32 v218, 16, v148
	v_and_b32_e32 v219, 0xffff0000, v148
	v_lshlrev_b32_e32 v220, 16, v149
	v_and_b32_e32 v221, 0xffff0000, v149
	v_pk_fma_f32 v[222:223], v[206:207], v[218:219], v[222:223]
	v_pk_fma_f32 v[224:225], v[208:209], v[220:221], v[224:225]
	v_lshlrev_b32_e32 v218, 16, v150
	v_and_b32_e32 v219, 0xffff0000, v150
	v_lshlrev_b32_e32 v220, 16, v151
	v_and_b32_e32 v221, 0xffff0000, v151
	v_pk_fma_f32 v[222:223], v[210:211], v[218:219], v[222:223]
	v_pk_fma_f32 v[224:225], v[212:213], v[220:221], v[224:225]
	v_lshlrev_b32_e32 v218, 16, v152
	v_and_b32_e32 v219, 0xffff0000, v152
	v_lshlrev_b32_e32 v220, 16, v153
	v_and_b32_e32 v221, 0xffff0000, v153
	v_pk_fma_f32 v[222:223], v[214:215], v[218:219], v[222:223]
	v_pk_fma_f32 v[224:225], v[216:217], v[220:221], v[224:225]
	v_mov_b32_e32 v230, v145
	v_cvt_pk_bf16_f32 v226, v222, v223
	v_cvt_pk_bf16_f32 v227, v224, v225
	global_store_dwordx2 v230, v[226:227], s[84:85]
	v_add_u32_e32 v170, 0x6000, v144
	global_load_dwordx2 v[146:147], v170, s[48:49]
	v_add_u32_e32 v171, 0x26000, v144
	global_load_dwordx2 v[148:149], v171, s[48:49]
	v_add_u32_e32 v172, 0x46000, v144
	global_load_dwordx2 v[150:151], v172, s[48:49]
	v_add_u32_e32 v173, 0x66000, v144
	global_load_dwordx2 v[152:153], v173, s[48:49]
	v_pk_mul_f32 v[174:175], v[118:119], s[100:101] op_sel_hi:[1,0]
	v_pk_mul_f32 v[182:183], v[120:121], s[100:101] op_sel_hi:[1,0]
	v_exp_f32_e32 v174, v174
	v_exp_f32_e32 v175, v175
	v_exp_f32_e32 v182, v182
	v_exp_f32_e32 v183, v183
	v_pk_add_f32 v[174:175], v[174:175], 1.0 op_sel_hi:[1,0]
	v_pk_add_f32 v[182:183], v[182:183], 1.0 op_sel_hi:[1,0]
	v_rcp_f32_e32 v202, v174
	v_rcp_f32_e32 v203, v175
	v_rcp_f32_e32 v204, v182
	v_rcp_f32_e32 v205, v183
	v_pk_mul_f32 v[174:175], v[114:115], s[100:101] op_sel_hi:[1,0]
	v_pk_mul_f32 v[182:183], v[116:117], s[100:101] op_sel_hi:[1,0]
	v_exp_f32_e32 v174, v174
	v_exp_f32_e32 v175, v175
	v_exp_f32_e32 v182, v182
	v_exp_f32_e32 v183, v183
	v_pk_add_f32 v[174:175], v[174:175], 1.0 op_sel_hi:[1,0]
	v_pk_add_f32 v[182:183], v[182:183], 1.0 op_sel_hi:[1,0]
	v_rcp_f32_e32 v206, v174
	v_rcp_f32_e32 v207, v175
	v_rcp_f32_e32 v208, v182
	v_rcp_f32_e32 v209, v183
	v_pk_mul_f32 v[174:175], v[86:87], s[100:101] op_sel_hi:[1,0]
	v_pk_mul_f32 v[182:183], v[88:89], s[100:101] op_sel_hi:[1,0]
	v_exp_f32_e32 v174, v174
	v_exp_f32_e32 v175, v175
	v_exp_f32_e32 v182, v182
	v_exp_f32_e32 v183, v183
	v_pk_add_f32 v[174:175], v[174:175], 1.0 op_sel_hi:[1,0]
	v_pk_add_f32 v[182:183], v[182:183], 1.0 op_sel_hi:[1,0]
	v_rcp_f32_e32 v210, v174
	v_rcp_f32_e32 v211, v175
	v_rcp_f32_e32 v212, v182
	v_rcp_f32_e32 v213, v183
	v_pk_mul_f32 v[174:175], v[82:83], s[100:101] op_sel_hi:[1,0]
	v_pk_mul_f32 v[182:183], v[84:85], s[100:101] op_sel_hi:[1,0]
	v_exp_f32_e32 v174, v174
	v_exp_f32_e32 v175, v175
	v_exp_f32_e32 v182, v182
	v_exp_f32_e32 v183, v183
	v_pk_add_f32 v[174:175], v[174:175], 1.0 op_sel_hi:[1,0]
	v_pk_add_f32 v[182:183], v[182:183], 1.0 op_sel_hi:[1,0]
	v_rcp_f32_e32 v214, v174
	v_rcp_f32_e32 v215, v175
	v_rcp_f32_e32 v216, v182
	v_rcp_f32_e32 v217, v183
	s_waitcnt vmcnt(9)
; __device__ __forceinline__ float lo2f(unsigned w) { return __uint_as_float(w << 16); }
; __device__ __forceinline__ float hi2f(unsigned w) { return __uint_as_float(w & 0xffff0000u); }
; __device__ __forceinline__ float sigm(float x) { return __builtin_amdgcn_rcpf(1.f + __expf(-x)); }
;   __device__ __forceinline__ void operator()(const f32x4 (&acc)[2][2][4][2], const Unit& u, int wr, int wc, int fr, int fq) const {
;     ...
;       const int q = s - 4, bjq = q >> 1, nq = q & 1;
; #pragma unroll
;       for (int ai = 0; ai < 2; ++ai)
; #pragma unroll
;         for (int m = 0; m < 4; ++m) {
;           float o[4] = {0.f, 0.f, 0.f, 0.f};
; #pragma unroll
;           for (int bj = 0; bj < 2; ++bj)
; #pragma unroll
;             for (int n = 0; n < 2; ++n) {
;               const int ib = 2 * bj + n;
;               const uint2 b2 = *(reinterpret_cast<const uint2*>(brs + (size_t)(ib * 16 + (ai * 2 + bjq) * 4 + m) * 512 + tid) + nq);
;               const f32x4 g = acc[ai][bj][m][n];
;               o[0] += sigm(g[0]) * lo2f(b2.x); o[1] += sigm(g[1]) * hi2f(b2.x);
;               o[2] += sigm(g[2]) * lo2f(b2.y); o[3] += sigm(g[3]) * hi2f(b2.y);
;             }
;           const int r = u.pm * 256 + ai * 128 + wr * 64 + m * 16 + fr;
;           const int d = dq * 256 + 64 * q + 16 * wc + 4 * fq;
;           uint2 w; w.x = pack2(o[0], o[1]); w.y = pack2(o[2], o[3]);
;           *reinterpret_cast<uint2*>(ACC + (size_t)r * 1024 + d) = w;
;         }
	v_lshlrev_b32_e32 v218, 16, v154
	v_and_b32_e32 v219, 0xffff0000, v154
	v_lshlrev_b32_e32 v220, 16, v155
	v_and_b32_e32 v221, 0xffff0000, v155
	v_pk_fma_f32 v[222:223], v[202:203], v[218:219], 0 op_sel_hi:[1,1,0]
	v_pk_fma_f32 v[224:225], v[204:205], v[220:221], 0 op_sel_hi:[1,1,0]
	v_lshlrev_b32_e32 v218, 16, v156
	v_and_b32_e32 v219, 0xffff0000, v156
	v_lshlrev_b32_e32 v220, 16, v157
	v_and_b32_e32 v221, 0xffff0000, v157
	v_pk_fma_f32 v[222:223], v[206:207], v[218:219], v[222:223]
	v_pk_fma_f32 v[224:225], v[208:209], v[220:221], v[224:225]
	v_lshlrev_b32_e32 v218, 16, v158
	v_and_b32_e32 v219, 0xffff0000, v158
	v_lshlrev_b32_e32 v220, 16, v159
	v_and_b32_e32 v221, 0xffff0000, v159
	v_pk_fma_f32 v[222:223], v[210:211], v[218:219], v[222:223]
	v_pk_fma_f32 v[224:225], v[212:213], v[220:221], v[224:225]
	v_lshlrev_b32_e32 v218, 16, v160
	v_and_b32_e32 v219, 0xffff0000, v160
	v_lshlrev_b32_e32 v220, 16, v161
	v_and_b32_e32 v221, 0xffff0000, v161
	v_pk_fma_f32 v[222:223], v[214:215], v[218:219], v[222:223]
	v_pk_fma_f32 v[224:225], v[216:217], v[220:221], v[224:225]
	v_add_u32_e32 v231, 0x8000, v145
	v_cvt_pk_bf16_f32 v228, v222, v223
	v_cvt_pk_bf16_f32 v229, v224, v225
	global_store_dwordx2 v231, v[228:229], s[84:85]
	v_add_u32_e32 v170, 0x10000, v144
	global_load_dwordx2 v[154:155], v170, s[48:49]
	v_add_u32_e32 v171, 0x30000, v144
	global_load_dwordx2 v[156:157], v171, s[48:49]
	v_add_u32_e32 v172, 0x50000, v144
	global_load_dwordx2 v[158:159], v172, s[48:49]
	v_add_u32_e32 v173, 0x70000, v144
	global_load_dwordx2 v[160:161], v173, s[48:49]
	v_pk_mul_f32 v[174:175], v[110:111], s[100:101] op_sel_hi:[1,0]
	v_pk_mul_f32 v[182:183], v[112:113], s[100:101] op_sel_hi:[1,0]
	v_exp_f32_e32 v174, v174
	v_exp_f32_e32 v175, v175
	v_exp_f32_e32 v182, v182
	v_exp_f32_e32 v183, v183
	v_pk_add_f32 v[174:175], v[174:175], 1.0 op_sel_hi:[1,0]
	v_pk_add_f32 v[182:183], v[182:183], 1.0 op_sel_hi:[1,0]
	v_rcp_f32_e32 v202, v174
	v_rcp_f32_e32 v203, v175
	v_rcp_f32_e32 v204, v182
	v_rcp_f32_e32 v205, v183
	v_pk_mul_f32 v[174:175], v[106:107], s[100:101] op_sel_hi:[1,0]
	v_pk_mul_f32 v[182:183], v[108:109], s[100:101] op_sel_hi:[1,0]
	v_exp_f32_e32 v174, v174
	v_exp_f32_e32 v175, v175
	v_exp_f32_e32 v182, v182
	v_exp_f32_e32 v183, v183
	v_pk_add_f32 v[174:175], v[174:175], 1.0 op_sel_hi:[1,0]
	v_pk_add_f32 v[182:183], v[182:183], 1.0 op_sel_hi:[1,0]
	v_rcp_f32_e32 v206, v174
	v_rcp_f32_e32 v207, v175
	v_rcp_f32_e32 v208, v182
	v_rcp_f32_e32 v209, v183
	v_pk_mul_f32 v[174:175], v[78:79], s[100:101] op_sel_hi:[1,0]
	v_pk_mul_f32 v[182:183], v[80:81], s[100:101] op_sel_hi:[1,0]
	v_exp_f32_e32 v174, v174
	v_exp_f32_e32 v175, v175
	v_exp_f32_e32 v182, v182
	v_exp_f32_e32 v183, v183
	v_pk_add_f32 v[174:175], v[174:175], 1.0 op_sel_hi:[1,0]
	v_pk_add_f32 v[182:183], v[182:183], 1.0 op_sel_hi:[1,0]
	v_rcp_f32_e32 v210, v174
	v_rcp_f32_e32 v211, v175
	v_rcp_f32_e32 v212, v182
	v_rcp_f32_e32 v213, v183
	v_pk_mul_f32 v[174:175], v[74:75], s[100:101] op_sel_hi:[1,0]
	v_pk_mul_f32 v[182:183], v[76:77], s[100:101] op_sel_hi:[1,0]
	v_exp_f32_e32 v174, v174
	v_exp_f32_e32 v175, v175
	v_exp_f32_e32 v182, v182
	v_exp_f32_e32 v183, v183
	v_pk_add_f32 v[174:175], v[174:175], 1.0 op_sel_hi:[1,0]
	v_pk_add_f32 v[182:183], v[182:183], 1.0 op_sel_hi:[1,0]
	v_rcp_f32_e32 v214, v174
	v_rcp_f32_e32 v215, v175
	v_rcp_f32_e32 v216, v182
	v_rcp_f32_e32 v217, v183
	s_waitcnt vmcnt(10)
	v_lshlrev_b32_e32 v218, 16, v162
	v_and_b32_e32 v219, 0xffff0000, v162
	v_lshlrev_b32_e32 v220, 16, v163
	v_and_b32_e32 v221, 0xffff0000, v163
	v_pk_fma_f32 v[222:223], v[202:203], v[218:219], 0 op_sel_hi:[1,1,0]
	v_pk_fma_f32 v[224:225], v[204:205], v[220:221], 0 op_sel_hi:[1,1,0]
	v_lshlrev_b32_e32 v218, 16, v164
	v_and_b32_e32 v219, 0xffff0000, v164
	v_lshlrev_b32_e32 v220, 16, v165
	v_and_b32_e32 v221, 0xffff0000, v165
	v_pk_fma_f32 v[222:223], v[206:207], v[218:219], v[222:223]
	v_pk_fma_f32 v[224:225], v[208:209], v[220:221], v[224:225]
	v_lshlrev_b32_e32 v218, 16, v166
	v_and_b32_e32 v219, 0xffff0000, v166
	v_lshlrev_b32_e32 v220, 16, v167
	v_and_b32_e32 v221, 0xffff0000, v167
	v_pk_fma_f32 v[222:223], v[210:211], v[218:219], v[222:223]
	v_pk_fma_f32 v[224:225], v[212:213], v[220:221], v[224:225]
	v_lshlrev_b32_e32 v218, 16, v168
	v_and_b32_e32 v219, 0xffff0000, v168
	v_lshlrev_b32_e32 v220, 16, v169
	v_and_b32_e32 v221, 0xffff0000, v169
	v_pk_fma_f32 v[222:223], v[214:215], v[218:219], v[222:223]
	v_pk_fma_f32 v[224:225], v[216:217], v[220:221], v[224:225]
	v_add_u32_e32 v230, 0x10000, v145
	v_cvt_pk_bf16_f32 v226, v222, v223
	v_cvt_pk_bf16_f32 v227, v224, v225
	global_store_dwordx2 v230, v[226:227], s[84:85]
	v_add_u32_e32 v170, 0x12000, v144
	global_load_dwordx2 v[162:163], v170, s[48:49]
	v_add_u32_e32 v171, 0x32000, v144
	global_load_dwordx2 v[164:165], v171, s[48:49]
	v_add_u32_e32 v172, 0x52000, v144
	global_load_dwordx2 v[166:167], v172, s[48:49]
	v_add_u32_e32 v173, 0x72000, v144
	global_load_dwordx2 v[168:169], v173, s[48:49]
	v_pk_mul_f32 v[174:175], v[102:103], s[100:101] op_sel_hi:[1,0]
	v_pk_mul_f32 v[182:183], v[104:105], s[100:101] op_sel_hi:[1,0]
	v_exp_f32_e32 v174, v174
	v_exp_f32_e32 v175, v175
	v_exp_f32_e32 v182, v182
	v_exp_f32_e32 v183, v183
	v_pk_add_f32 v[174:175], v[174:175], 1.0 op_sel_hi:[1,0]
	v_pk_add_f32 v[182:183], v[182:183], 1.0 op_sel_hi:[1,0]
	v_rcp_f32_e32 v202, v174
	v_rcp_f32_e32 v203, v175
	v_rcp_f32_e32 v204, v182
	v_rcp_f32_e32 v205, v183
	v_pk_mul_f32 v[174:175], v[98:99], s[100:101] op_sel_hi:[1,0]
	v_pk_mul_f32 v[182:183], v[100:101], s[100:101] op_sel_hi:[1,0]
	v_exp_f32_e32 v174, v174
	v_exp_f32_e32 v175, v175
	v_exp_f32_e32 v182, v182
	v_exp_f32_e32 v183, v183
	v_pk_add_f32 v[174:175], v[174:175], 1.0 op_sel_hi:[1,0]
	v_pk_add_f32 v[182:183], v[182:183], 1.0 op_sel_hi:[1,0]
	v_rcp_f32_e32 v206, v174
	v_rcp_f32_e32 v207, v175
	v_rcp_f32_e32 v208, v182
	v_rcp_f32_e32 v209, v183
	v_pk_mul_f32 v[174:175], v[70:71], s[100:101] op_sel_hi:[1,0]
	v_pk_mul_f32 v[182:183], v[72:73], s[100:101] op_sel_hi:[1,0]
	v_exp_f32_e32 v174, v174
	v_exp_f32_e32 v175, v175
	v_exp_f32_e32 v182, v182
	v_exp_f32_e32 v183, v183
	v_pk_add_f32 v[174:175], v[174:175], 1.0 op_sel_hi:[1,0]
	v_pk_add_f32 v[182:183], v[182:183], 1.0 op_sel_hi:[1,0]
	v_rcp_f32_e32 v210, v174
	v_rcp_f32_e32 v211, v175
	v_rcp_f32_e32 v212, v182
	v_rcp_f32_e32 v213, v183
	v_pk_mul_f32 v[174:175], v[66:67], s[100:101] op_sel_hi:[1,0]
	v_pk_mul_f32 v[182:183], v[68:69], s[100:101] op_sel_hi:[1,0]
	v_exp_f32_e32 v174, v174
	v_exp_f32_e32 v175, v175
	v_exp_f32_e32 v182, v182
	v_exp_f32_e32 v183, v183
	v_pk_add_f32 v[174:175], v[174:175], 1.0 op_sel_hi:[1,0]
	v_pk_add_f32 v[182:183], v[182:183], 1.0 op_sel_hi:[1,0]
	v_rcp_f32_e32 v214, v174
	v_rcp_f32_e32 v215, v175
	v_rcp_f32_e32 v216, v182
	v_rcp_f32_e32 v217, v183
	s_waitcnt vmcnt(10)
; __device__ __forceinline__ float lo2f(unsigned w) { return __uint_as_float(w << 16); }
; __device__ __forceinline__ float hi2f(unsigned w) { return __uint_as_float(w & 0xffff0000u); }
; __device__ __forceinline__ float sigm(float x) { return __builtin_amdgcn_rcpf(1.f + __expf(-x)); }
;   __device__ __forceinline__ void operator()(const f32x4 (&acc)[2][2][4][2], const Unit& u, int wr, int wc, int fr, int fq) const {
;     ...
;       const int q = s - 4, bjq = q >> 1, nq = q & 1;
; #pragma unroll
;       for (int ai = 0; ai < 2; ++ai)
; #pragma unroll
;         for (int m = 0; m < 4; ++m) {
;           float o[4] = {0.f, 0.f, 0.f, 0.f};
; #pragma unroll
;           for (int bj = 0; bj < 2; ++bj)
; #pragma unroll
;             for (int n = 0; n < 2; ++n) {
;               const int ib = 2 * bj + n;
;               const uint2 b2 = *(reinterpret_cast<const uint2*>(brs + (size_t)(ib * 16 + (ai * 2 + bjq) * 4 + m) * 512 + tid) + nq);
;               const f32x4 g = acc[ai][bj][m][n];
;               o[0] += sigm(g[0]) * lo2f(b2.x); o[1] += sigm(g[1]) * hi2f(b2.x);
;               o[2] += sigm(g[2]) * lo2f(b2.y); o[3] += sigm(g[3]) * hi2f(b2.y);
;             }
;           const int r = u.pm * 256 + ai * 128 + wr * 64 + m * 16 + fr;
;           const int d = dq * 256 + 64 * q + 16 * wc + 4 * fq;
;           uint2 w; w.x = pack2(o[0], o[1]); w.y = pack2(o[2], o[3]);
;           *reinterpret_cast<uint2*>(ACC + (size_t)r * 1024 + d) = w;
;         }
	v_lshlrev_b32_e32 v218, 16, v146
	v_and_b32_e32 v219, 0xffff0000, v146
	v_lshlrev_b32_e32 v220, 16, v147
	v_and_b32_e32 v221, 0xffff0000, v147
	v_pk_fma_f32 v[222:223], v[202:203], v[218:219], 0 op_sel_hi:[1,1,0]
	v_pk_fma_f32 v[224:225], v[204:205], v[220:221], 0 op_sel_hi:[1,1,0]
	v_lshlrev_b32_e32 v218, 16, v148
	v_and_b32_e32 v219, 0xffff0000, v148
	v_lshlrev_b32_e32 v220, 16, v149
	v_and_b32_e32 v221, 0xffff0000, v149
	v_pk_fma_f32 v[222:223], v[206:207], v[218:219], v[222:223]
	v_pk_fma_f32 v[224:225], v[208:209], v[220:221], v[224:225]
	v_lshlrev_b32_e32 v218, 16, v150
	v_and_b32_e32 v219, 0xffff0000, v150
	v_lshlrev_b32_e32 v220, 16, v151
	v_and_b32_e32 v221, 0xffff0000, v151
	v_pk_fma_f32 v[222:223], v[210:211], v[218:219], v[222:223]
	v_pk_fma_f32 v[224:225], v[212:213], v[220:221], v[224:225]
	v_lshlrev_b32_e32 v218, 16, v152
	v_and_b32_e32 v219, 0xffff0000, v152
	v_lshlrev_b32_e32 v220, 16, v153
	v_and_b32_e32 v221, 0xffff0000, v153
	v_pk_fma_f32 v[222:223], v[214:215], v[218:219], v[222:223]
	v_pk_fma_f32 v[224:225], v[216:217], v[220:221], v[224:225]
	v_add_u32_e32 v231, 0x18000, v145
	v_cvt_pk_bf16_f32 v228, v222, v223
	v_cvt_pk_bf16_f32 v229, v224, v225
	global_store_dwordx2 v231, v[228:229], s[84:85]
	v_add_u32_e32 v170, 0x14000, v144
	global_load_dwordx2 v[146:147], v170, s[48:49]
	v_add_u32_e32 v171, 0x34000, v144
	global_load_dwordx2 v[148:149], v171, s[48:49]
	v_add_u32_e32 v172, 0x54000, v144
	global_load_dwordx2 v[150:151], v172, s[48:49]
	v_add_u32_e32 v173, 0x74000, v144
	global_load_dwordx2 v[152:153], v173, s[48:49]
	v_pk_mul_f32 v[174:175], v[62:63], s[100:101] op_sel_hi:[1,0]
	v_pk_mul_f32 v[182:183], v[64:65], s[100:101] op_sel_hi:[1,0]
	v_exp_f32_e32 v174, v174
	v_exp_f32_e32 v175, v175
	v_exp_f32_e32 v182, v182
	v_exp_f32_e32 v183, v183
	v_pk_add_f32 v[174:175], v[174:175], 1.0 op_sel_hi:[1,0]
	v_pk_add_f32 v[182:183], v[182:183], 1.0 op_sel_hi:[1,0]
	v_rcp_f32_e32 v202, v174
	v_rcp_f32_e32 v203, v175
	v_rcp_f32_e32 v204, v182
	v_rcp_f32_e32 v205, v183
	v_pk_mul_f32 v[174:175], v[58:59], s[100:101] op_sel_hi:[1,0]
	v_pk_mul_f32 v[182:183], v[60:61], s[100:101] op_sel_hi:[1,0]
	v_exp_f32_e32 v174, v174
	v_exp_f32_e32 v175, v175
	v_exp_f32_e32 v182, v182
	v_exp_f32_e32 v183, v183
	v_pk_add_f32 v[174:175], v[174:175], 1.0 op_sel_hi:[1,0]
	v_pk_add_f32 v[182:183], v[182:183], 1.0 op_sel_hi:[1,0]
	v_rcp_f32_e32 v206, v174
	v_rcp_f32_e32 v207, v175
	v_rcp_f32_e32 v208, v182
	v_rcp_f32_e32 v209, v183
	v_pk_mul_f32 v[174:175], v[30:31], s[100:101] op_sel_hi:[1,0]
	v_pk_mul_f32 v[182:183], v[32:33], s[100:101] op_sel_hi:[1,0]
	v_exp_f32_e32 v174, v174
	v_exp_f32_e32 v175, v175
	v_exp_f32_e32 v182, v182
	v_exp_f32_e32 v183, v183
	v_pk_add_f32 v[174:175], v[174:175], 1.0 op_sel_hi:[1,0]
	v_pk_add_f32 v[182:183], v[182:183], 1.0 op_sel_hi:[1,0]
	v_rcp_f32_e32 v210, v174
	v_rcp_f32_e32 v211, v175
	v_rcp_f32_e32 v212, v182
	v_rcp_f32_e32 v213, v183
	v_pk_mul_f32 v[174:175], v[26:27], s[100:101] op_sel_hi:[1,0]
	v_pk_mul_f32 v[182:183], v[28:29], s[100:101] op_sel_hi:[1,0]
	v_exp_f32_e32 v174, v174
	v_exp_f32_e32 v175, v175
	v_exp_f32_e32 v182, v182
	v_exp_f32_e32 v183, v183
	v_pk_add_f32 v[174:175], v[174:175], 1.0 op_sel_hi:[1,0]
	v_pk_add_f32 v[182:183], v[182:183], 1.0 op_sel_hi:[1,0]
	v_rcp_f32_e32 v214, v174
	v_rcp_f32_e32 v215, v175
	v_rcp_f32_e32 v216, v182
	v_rcp_f32_e32 v217, v183
	s_waitcnt vmcnt(10)
	v_lshlrev_b32_e32 v218, 16, v154
	v_and_b32_e32 v219, 0xffff0000, v154
	v_lshlrev_b32_e32 v220, 16, v155
	v_and_b32_e32 v221, 0xffff0000, v155
	v_pk_fma_f32 v[222:223], v[202:203], v[218:219], 0 op_sel_hi:[1,1,0]
	v_pk_fma_f32 v[224:225], v[204:205], v[220:221], 0 op_sel_hi:[1,1,0]
	v_lshlrev_b32_e32 v218, 16, v156
	v_and_b32_e32 v219, 0xffff0000, v156
	v_lshlrev_b32_e32 v220, 16, v157
	v_and_b32_e32 v221, 0xffff0000, v157
	v_pk_fma_f32 v[222:223], v[206:207], v[218:219], v[222:223]
	v_pk_fma_f32 v[224:225], v[208:209], v[220:221], v[224:225]
	v_lshlrev_b32_e32 v218, 16, v158
	v_and_b32_e32 v219, 0xffff0000, v158
	v_lshlrev_b32_e32 v220, 16, v159
	v_and_b32_e32 v221, 0xffff0000, v159
	v_pk_fma_f32 v[222:223], v[210:211], v[218:219], v[222:223]
	v_pk_fma_f32 v[224:225], v[212:213], v[220:221], v[224:225]
	v_lshlrev_b32_e32 v218, 16, v160
	v_and_b32_e32 v219, 0xffff0000, v160
	v_lshlrev_b32_e32 v220, 16, v161
	v_and_b32_e32 v221, 0xffff0000, v161
	v_pk_fma_f32 v[222:223], v[214:215], v[218:219], v[222:223]
	v_pk_fma_f32 v[224:225], v[216:217], v[220:221], v[224:225]
	v_add_u32_e32 v230, 0x40000, v145
	v_cvt_pk_bf16_f32 v226, v222, v223
	v_cvt_pk_bf16_f32 v227, v224, v225
	global_store_dwordx2 v230, v[226:227], s[84:85]
	v_add_u32_e32 v170, 0x16000, v144
	global_load_dwordx2 v[154:155], v170, s[48:49]
	v_add_u32_e32 v171, 0x36000, v144
	global_load_dwordx2 v[156:157], v171, s[48:49]
	v_add_u32_e32 v172, 0x56000, v144
	global_load_dwordx2 v[158:159], v172, s[48:49]
	v_add_u32_e32 v173, 0x76000, v144
	global_load_dwordx2 v[160:161], v173, s[48:49]
	v_pk_mul_f32 v[174:175], v[54:55], s[100:101] op_sel_hi:[1,0]
	v_pk_mul_f32 v[182:183], v[56:57], s[100:101] op_sel_hi:[1,0]
	v_exp_f32_e32 v174, v174
	v_exp_f32_e32 v175, v175
	v_exp_f32_e32 v182, v182
	v_exp_f32_e32 v183, v183
	v_pk_add_f32 v[174:175], v[174:175], 1.0 op_sel_hi:[1,0]
	v_pk_add_f32 v[182:183], v[182:183], 1.0 op_sel_hi:[1,0]
	v_rcp_f32_e32 v202, v174
	v_rcp_f32_e32 v203, v175
	v_rcp_f32_e32 v204, v182
	v_rcp_f32_e32 v205, v183
	v_pk_mul_f32 v[174:175], v[50:51], s[100:101] op_sel_hi:[1,0]
	v_pk_mul_f32 v[182:183], v[52:53], s[100:101] op_sel_hi:[1,0]
	v_exp_f32_e32 v174, v174
	v_exp_f32_e32 v175, v175
	v_exp_f32_e32 v182, v182
	v_exp_f32_e32 v183, v183
	v_pk_add_f32 v[174:175], v[174:175], 1.0 op_sel_hi:[1,0]
	v_pk_add_f32 v[182:183], v[182:183], 1.0 op_sel_hi:[1,0]
	v_rcp_f32_e32 v206, v174
	v_rcp_f32_e32 v207, v175
	v_rcp_f32_e32 v208, v182
	v_rcp_f32_e32 v209, v183
	v_pk_mul_f32 v[174:175], v[22:23], s[100:101] op_sel_hi:[1,0]
	v_pk_mul_f32 v[182:183], v[24:25], s[100:101] op_sel_hi:[1,0]
	v_exp_f32_e32 v174, v174
	v_exp_f32_e32 v175, v175
	v_exp_f32_e32 v182, v182
	v_exp_f32_e32 v183, v183
	v_pk_add_f32 v[174:175], v[174:175], 1.0 op_sel_hi:[1,0]
	v_pk_add_f32 v[182:183], v[182:183], 1.0 op_sel_hi:[1,0]
	v_rcp_f32_e32 v210, v174
	v_rcp_f32_e32 v211, v175
	v_rcp_f32_e32 v212, v182
	v_rcp_f32_e32 v213, v183
	v_pk_mul_f32 v[174:175], v[18:19], s[100:101] op_sel_hi:[1,0]
	v_pk_mul_f32 v[182:183], v[20:21], s[100:101] op_sel_hi:[1,0]
	v_exp_f32_e32 v174, v174
	v_exp_f32_e32 v175, v175
	v_exp_f32_e32 v182, v182
	v_exp_f32_e32 v183, v183
	v_pk_add_f32 v[174:175], v[174:175], 1.0 op_sel_hi:[1,0]
	v_pk_add_f32 v[182:183], v[182:183], 1.0 op_sel_hi:[1,0]
	v_rcp_f32_e32 v214, v174
	v_rcp_f32_e32 v215, v175
	v_rcp_f32_e32 v216, v182
	v_rcp_f32_e32 v217, v183
	s_waitcnt vmcnt(10)
; __device__ __forceinline__ float lo2f(unsigned w) { return __uint_as_float(w << 16); }
; __device__ __forceinline__ float hi2f(unsigned w) { return __uint_as_float(w & 0xffff0000u); }
; __device__ __forceinline__ float sigm(float x) { return __builtin_amdgcn_rcpf(1.f + __expf(-x)); }
;   __device__ __forceinline__ void operator()(const f32x4 (&acc)[2][2][4][2], const Unit& u, int wr, int wc, int fr, int fq) const {
;     ...
;       const int q = s - 4, bjq = q >> 1, nq = q & 1;
; #pragma unroll
;       for (int ai = 0; ai < 2; ++ai)
; #pragma unroll
;         for (int m = 0; m < 4; ++m) {
;           float o[4] = {0.f, 0.f, 0.f, 0.f};
; #pragma unroll
;           for (int bj = 0; bj < 2; ++bj)
; #pragma unroll
;             for (int n = 0; n < 2; ++n) {
;               const int ib = 2 * bj + n;
;               const uint2 b2 = *(reinterpret_cast<const uint2*>(brs + (size_t)(ib * 16 + (ai * 2 + bjq) * 4 + m) * 512 + tid) + nq);
;               const f32x4 g = acc[ai][bj][m][n];
;               o[0] += sigm(g[0]) * lo2f(b2.x); o[1] += sigm(g[1]) * hi2f(b2.x);
;               o[2] += sigm(g[2]) * lo2f(b2.y); o[3] += sigm(g[3]) * hi2f(b2.y);
;             }
;           const int r = u.pm * 256 + ai * 128 + wr * 64 + m * 16 + fr;
;           const int d = dq * 256 + 64 * q + 16 * wc + 4 * fq;
;           uint2 w; w.x = pack2(o[0], o[1]); w.y = pack2(o[2], o[3]);
;           *reinterpret_cast<uint2*>(ACC + (size_t)r * 1024 + d) = w;
;         }
	v_lshlrev_b32_e32 v218, 16, v162
	v_and_b32_e32 v219, 0xffff0000, v162
	v_lshlrev_b32_e32 v220, 16, v163
	v_and_b32_e32 v221, 0xffff0000, v163
	v_pk_fma_f32 v[222:223], v[202:203], v[218:219], 0 op_sel_hi:[1,1,0]
	v_pk_fma_f32 v[224:225], v[204:205], v[220:221], 0 op_sel_hi:[1,1,0]
	v_lshlrev_b32_e32 v218, 16, v164
	v_and_b32_e32 v219, 0xffff0000, v164
	v_lshlrev_b32_e32 v220, 16, v165
	v_and_b32_e32 v221, 0xffff0000, v165
	v_pk_fma_f32 v[222:223], v[206:207], v[218:219], v[222:223]
	v_pk_fma_f32 v[224:225], v[208:209], v[220:221], v[224:225]
	v_lshlrev_b32_e32 v218, 16, v166
	v_and_b32_e32 v219, 0xffff0000, v166
	v_lshlrev_b32_e32 v220, 16, v167
	v_and_b32_e32 v221, 0xffff0000, v167
	v_pk_fma_f32 v[222:223], v[210:211], v[218:219], v[222:223]
	v_pk_fma_f32 v[224:225], v[212:213], v[220:221], v[224:225]
	v_lshlrev_b32_e32 v218, 16, v168
	v_and_b32_e32 v219, 0xffff0000, v168
	v_lshlrev_b32_e32 v220, 16, v169
	v_and_b32_e32 v221, 0xffff0000, v169
	v_pk_fma_f32 v[222:223], v[214:215], v[218:219], v[222:223]
	v_pk_fma_f32 v[224:225], v[216:217], v[220:221], v[224:225]
	v_add_u32_e32 v231, 0x48000, v145
	v_cvt_pk_bf16_f32 v228, v222, v223
	v_cvt_pk_bf16_f32 v229, v224, v225
	global_store_dwordx2 v231, v[228:229], s[84:85]
	v_pk_mul_f32 v[174:175], v[46:47], s[100:101] op_sel_hi:[1,0]
	v_pk_mul_f32 v[182:183], v[48:49], s[100:101] op_sel_hi:[1,0]
	v_exp_f32_e32 v174, v174
	v_exp_f32_e32 v175, v175
	v_exp_f32_e32 v182, v182
	v_exp_f32_e32 v183, v183
	v_pk_add_f32 v[174:175], v[174:175], 1.0 op_sel_hi:[1,0]
	v_pk_add_f32 v[182:183], v[182:183], 1.0 op_sel_hi:[1,0]
	v_rcp_f32_e32 v202, v174
	v_rcp_f32_e32 v203, v175
	v_rcp_f32_e32 v204, v182
	v_rcp_f32_e32 v205, v183
	v_pk_mul_f32 v[174:175], v[42:43], s[100:101] op_sel_hi:[1,0]
	v_pk_mul_f32 v[182:183], v[44:45], s[100:101] op_sel_hi:[1,0]
	v_exp_f32_e32 v174, v174
	v_exp_f32_e32 v175, v175
	v_exp_f32_e32 v182, v182
	v_exp_f32_e32 v183, v183
	v_pk_add_f32 v[174:175], v[174:175], 1.0 op_sel_hi:[1,0]
	v_pk_add_f32 v[182:183], v[182:183], 1.0 op_sel_hi:[1,0]
	v_rcp_f32_e32 v206, v174
	v_rcp_f32_e32 v207, v175
	v_rcp_f32_e32 v208, v182
	v_rcp_f32_e32 v209, v183
	v_pk_mul_f32 v[174:175], v[14:15], s[100:101] op_sel_hi:[1,0]
	v_pk_mul_f32 v[182:183], v[16:17], s[100:101] op_sel_hi:[1,0]
	v_exp_f32_e32 v174, v174
	v_exp_f32_e32 v175, v175
	v_exp_f32_e32 v182, v182
	v_exp_f32_e32 v183, v183
	v_pk_add_f32 v[174:175], v[174:175], 1.0 op_sel_hi:[1,0]
	v_pk_add_f32 v[182:183], v[182:183], 1.0 op_sel_hi:[1,0]
	v_rcp_f32_e32 v210, v174
	v_rcp_f32_e32 v211, v175
	v_rcp_f32_e32 v212, v182
	v_rcp_f32_e32 v213, v183
	v_pk_mul_f32 v[174:175], v[10:11], s[100:101] op_sel_hi:[1,0]
	v_pk_mul_f32 v[182:183], v[12:13], s[100:101] op_sel_hi:[1,0]
	v_exp_f32_e32 v174, v174
	v_exp_f32_e32 v175, v175
	v_exp_f32_e32 v182, v182
	v_exp_f32_e32 v183, v183
	v_pk_add_f32 v[174:175], v[174:175], 1.0 op_sel_hi:[1,0]
	v_pk_add_f32 v[182:183], v[182:183], 1.0 op_sel_hi:[1,0]
	v_rcp_f32_e32 v214, v174
	v_rcp_f32_e32 v215, v175
	v_rcp_f32_e32 v216, v182
	v_rcp_f32_e32 v217, v183
	s_waitcnt vmcnt(6)
; __device__ __forceinline__ float lo2f(unsigned w) { return __uint_as_float(w << 16); }
; __device__ __forceinline__ float hi2f(unsigned w) { return __uint_as_float(w & 0xffff0000u); }
; __device__ __forceinline__ float sigm(float x) { return __builtin_amdgcn_rcpf(1.f + __expf(-x)); }
;   __device__ __forceinline__ void operator()(const f32x4 (&acc)[2][2][4][2], const Unit& u, int wr, int wc, int fr, int fq) const {
;     ...
;       const int q = s - 4, bjq = q >> 1, nq = q & 1;
; #pragma unroll
;       for (int ai = 0; ai < 2; ++ai)
; #pragma unroll
;         for (int m = 0; m < 4; ++m) {
;           float o[4] = {0.f, 0.f, 0.f, 0.f};
; #pragma unroll
;           for (int bj = 0; bj < 2; ++bj)
; #pragma unroll
;             for (int n = 0; n < 2; ++n) {
;               const int ib = 2 * bj + n;
;               const uint2 b2 = *(reinterpret_cast<const uint2*>(brs + (size_t)(ib * 16 + (ai * 2 + bjq) * 4 + m) * 512 + tid) + nq);
;               const f32x4 g = acc[ai][bj][m][n];
;               o[0] += sigm(g[0]) * lo2f(b2.x); o[1] += sigm(g[1]) * hi2f(b2.x);
;               o[2] += sigm(g[2]) * lo2f(b2.y); o[3] += sigm(g[3]) * hi2f(b2.y);
;             }
;           const int r = u.pm * 256 + ai * 128 + wr * 64 + m * 16 + fr;
;           const int d = dq * 256 + 64 * q + 16 * wc + 4 * fq;
;           uint2 w; w.x = pack2(o[0], o[1]); w.y = pack2(o[2], o[3]);
;           *reinterpret_cast<uint2*>(ACC + (size_t)r * 1024 + d) = w;
;         }
	v_lshlrev_b32_e32 v218, 16, v146
	v_and_b32_e32 v219, 0xffff0000, v146
	v_lshlrev_b32_e32 v220, 16, v147
	v_and_b32_e32 v221, 0xffff0000, v147
	v_pk_fma_f32 v[222:223], v[202:203], v[218:219], 0 op_sel_hi:[1,1,0]
	v_pk_fma_f32 v[224:225], v[204:205], v[220:221], 0 op_sel_hi:[1,1,0]
	v_lshlrev_b32_e32 v218, 16, v148
	v_and_b32_e32 v219, 0xffff0000, v148
	v_lshlrev_b32_e32 v220, 16, v149
	v_and_b32_e32 v221, 0xffff0000, v149
	v_pk_fma_f32 v[222:223], v[206:207], v[218:219], v[222:223]
	v_pk_fma_f32 v[224:225], v[208:209], v[220:221], v[224:225]
	v_lshlrev_b32_e32 v218, 16, v150
	v_and_b32_e32 v219, 0xffff0000, v150
	v_lshlrev_b32_e32 v220, 16, v151
	v_and_b32_e32 v221, 0xffff0000, v151
	v_pk_fma_f32 v[222:223], v[210:211], v[218:219], v[222:223]
	v_pk_fma_f32 v[224:225], v[212:213], v[220:221], v[224:225]
	v_lshlrev_b32_e32 v218, 16, v152
	v_and_b32_e32 v219, 0xffff0000, v152
	v_lshlrev_b32_e32 v220, 16, v153
	v_and_b32_e32 v221, 0xffff0000, v153
	v_pk_fma_f32 v[222:223], v[214:215], v[218:219], v[222:223]
	v_pk_fma_f32 v[224:225], v[216:217], v[220:221], v[224:225]
	v_add_u32_e32 v230, 0x50000, v145
	v_cvt_pk_bf16_f32 v226, v222, v223
	v_cvt_pk_bf16_f32 v227, v224, v225
	global_store_dwordx2 v230, v[226:227], s[84:85]
	v_pk_mul_f32 v[174:175], v[38:39], s[100:101] op_sel_hi:[1,0]
	v_pk_mul_f32 v[182:183], v[40:41], s[100:101] op_sel_hi:[1,0]
	v_exp_f32_e32 v174, v174
	v_exp_f32_e32 v175, v175
	v_exp_f32_e32 v182, v182
	v_exp_f32_e32 v183, v183
	v_pk_add_f32 v[174:175], v[174:175], 1.0 op_sel_hi:[1,0]
	v_pk_add_f32 v[182:183], v[182:183], 1.0 op_sel_hi:[1,0]
	v_rcp_f32_e32 v202, v174
	v_rcp_f32_e32 v203, v175
	v_rcp_f32_e32 v204, v182
	v_rcp_f32_e32 v205, v183
	v_pk_mul_f32 v[174:175], v[34:35], s[100:101] op_sel_hi:[1,0]
	v_pk_mul_f32 v[182:183], v[36:37], s[100:101] op_sel_hi:[1,0]
	v_exp_f32_e32 v174, v174
	v_exp_f32_e32 v175, v175
	v_exp_f32_e32 v182, v182
	v_exp_f32_e32 v183, v183
	v_pk_add_f32 v[174:175], v[174:175], 1.0 op_sel_hi:[1,0]
	v_pk_add_f32 v[182:183], v[182:183], 1.0 op_sel_hi:[1,0]
	v_rcp_f32_e32 v206, v174
	v_rcp_f32_e32 v207, v175
	v_rcp_f32_e32 v208, v182
	v_rcp_f32_e32 v209, v183
	v_pk_mul_f32 v[174:175], v[6:7], s[100:101] op_sel_hi:[1,0]
	v_pk_mul_f32 v[182:183], v[8:9], s[100:101] op_sel_hi:[1,0]
	v_exp_f32_e32 v174, v174
	v_exp_f32_e32 v175, v175
	v_exp_f32_e32 v182, v182
	v_exp_f32_e32 v183, v183
	v_pk_add_f32 v[174:175], v[174:175], 1.0 op_sel_hi:[1,0]
	v_pk_add_f32 v[182:183], v[182:183], 1.0 op_sel_hi:[1,0]
	v_rcp_f32_e32 v210, v174
	v_rcp_f32_e32 v211, v175
	v_rcp_f32_e32 v212, v182
	v_rcp_f32_e32 v213, v183
	v_pk_mul_f32 v[174:175], v[2:3], s[100:101] op_sel_hi:[1,0]
	v_pk_mul_f32 v[182:183], v[4:5], s[100:101] op_sel_hi:[1,0]
	v_exp_f32_e32 v174, v174
	v_exp_f32_e32 v175, v175
	v_exp_f32_e32 v182, v182
	v_exp_f32_e32 v183, v183
	v_pk_add_f32 v[174:175], v[174:175], 1.0 op_sel_hi:[1,0]
	v_pk_add_f32 v[182:183], v[182:183], 1.0 op_sel_hi:[1,0]
	v_rcp_f32_e32 v214, v174
	v_rcp_f32_e32 v215, v175
	v_rcp_f32_e32 v216, v182
	v_rcp_f32_e32 v217, v183
	s_waitcnt vmcnt(2)
	v_lshlrev_b32_e32 v218, 16, v154
	v_and_b32_e32 v219, 0xffff0000, v154
	v_lshlrev_b32_e32 v220, 16, v155
	v_and_b32_e32 v221, 0xffff0000, v155
	v_pk_fma_f32 v[222:223], v[202:203], v[218:219], 0 op_sel_hi:[1,1,0]
	v_pk_fma_f32 v[224:225], v[204:205], v[220:221], 0 op_sel_hi:[1,1,0]
	v_lshlrev_b32_e32 v218, 16, v156
	v_and_b32_e32 v219, 0xffff0000, v156
	v_lshlrev_b32_e32 v220, 16, v157
	v_and_b32_e32 v221, 0xffff0000, v157
	v_pk_fma_f32 v[222:223], v[206:207], v[218:219], v[222:223]
	v_pk_fma_f32 v[224:225], v[208:209], v[220:221], v[224:225]
	v_lshlrev_b32_e32 v218, 16, v158
	v_and_b32_e32 v219, 0xffff0000, v158
	v_lshlrev_b32_e32 v220, 16, v159
	v_and_b32_e32 v221, 0xffff0000, v159
	v_pk_fma_f32 v[222:223], v[210:211], v[218:219], v[222:223]
	v_pk_fma_f32 v[224:225], v[212:213], v[220:221], v[224:225]
	v_lshlrev_b32_e32 v218, 16, v160
	v_and_b32_e32 v219, 0xffff0000, v160
	v_lshlrev_b32_e32 v220, 16, v161
	v_and_b32_e32 v221, 0xffff0000, v161
	v_pk_fma_f32 v[222:223], v[214:215], v[218:219], v[222:223]
	v_pk_fma_f32 v[224:225], v[216:217], v[220:221], v[224:225]
	v_add_u32_e32 v231, 0x58000, v145
	v_cvt_pk_bf16_f32 v228, v222, v223
	v_cvt_pk_bf16_f32 v229, v224, v225
	global_store_dwordx2 v231, v[228:229], s[84:85]
	s_cbranch_execnz .LBB0_1415

; #define PG8_STAGE(bufoff, gbase, voff) do { _Pragma("unroll") for (int _i = 0; _i < 2; ++_i) \
;     __builtin_amdgcn_global_load_lds((const unsigned*)((const char*)(gbase) + (voff)[_i]), (PG8_LAS unsigned*)(lds + (bufoff) + ldsw + _i * 8192), 16, 0, 0); } while (0)
; #define PG8_LDA(dst, b, h) do { _Pragma("unroll") for (int m = 0; m < 4; ++m) _Pragma("unroll") for (int k = 0; k < 2; ++k) dst[m][k] = *(const PG8_LAS bf16x8*)(lds + PG8_SA(b, h) + aoff + m * 2048 + k * 1024); } while (0)
; #define PG8_LDB(dst, b, h) do { _Pragma("unroll") for (int n = 0; n < 2; ++n) _Pragma("unroll") for (int k = 0; k < 2; ++k) dst[n][k] = *(const PG8_LAS bf16x8*)(lds + PG8_SB(b, h) + boff + n * 2048 + k * 1024); } while (0)
; #define PG8_MMA(ai, bj, At, Bt) do { __builtin_amdgcn_s_setprio(1); _Pragma("unroll") for (int m = 0; m < 4; ++m) _Pragma("unroll") for (int n = 0; n < 2; ++n) _Pragma("unroll") for (int k = 0; k < 2; ++k) \
;     acc[ai][bj][m][n] = __builtin_amdgcn_mfma_f32_16x16x32_bf16(Bt[n][k], At[m][k], acc[ai][bj][m][n], 0, 0, 0); __builtin_amdgcn_s_setprio(0); } while (0)
; #define PG8_WAIT_V(n) asm volatile("s_waitcnt vmcnt(" #n ")" ::: "memory")
; #define PG8_WAIT_L(n) asm volatile("s_waitcnt lgkmcnt(" #n ")" ::: "memory")
; #define PG8_BAR __builtin_amdgcn_s_barrier()
; #define PG8_SCHED __builtin_amdgcn_sched_barrier(0)
; template <class Epi, class Sched>
; __device__ __forceinline__ void gemm_phase(PG8_LAS unsigned char* lds, const int lda, const int ldb, const Sched& S, const Epi& E) {
;     ...
;       PG8_LDB(B0, 0, 0); PG8_SCHED; PG8_LDA(At, 0, 0); PG8_STAGE(PG8_SA(1, 1), a1 + hstepA, voffA);
;       PG8_WAIT_L(8); PG8_BAR; PG8_WAIT_L(0); PG8_MMA(0, 0, At, B0); PG8_BAR; PG8_SCHED;
;       PG8_LDB(B1, 0, 1); PG8_STAGE(PG8_SB(0, 0), b2, voffB);
;       PG8_BAR; PG8_WAIT_L(0); PG8_MMA(0, 1, At, B1); PG8_BAR;
;       PG8_LDA(At, 0, 1); PG8_STAGE(PG8_SA(0, 0), a2, voffA);
;       PG8_BAR; PG8_WAIT_L(0); PG8_MMA(1, 0, At, B0); PG8_BAR; PG8_SCHED;
;       PG8_STAGE(PG8_SB(0, 1), b2 + hstepB, voffB);
;       PG8_WAIT_V(6); PG8_BAR; PG8_MMA(1, 1, At, B1); PG8_BAR;
.LBB0_1604:
	s_add_u32 s20, s18, 0xfffc0080
	s_addc_u32 s21, s19, -1
	s_add_i32 s33, 0, 0x10000
	v_add_u32_e32 v154, s33, v131
	ds_read_b128 v[142:145], v154
	ds_read_b128 v[146:149], v154 offset:1024
	ds_read_b128 v[150:153], v154 offset:2048
	ds_read_b128 v[154:157], v154 offset:3072
	s_cmp_eq_u32 s46, 12
	s_cselect_b32 s23, s11, s21
	s_cselect_b32 s22, s42, s20
	s_cselect_b32 s21, s1, s45
	s_cselect_b32 s20, s43, s44
	v_lshl_add_u64 v[174:175], s[18:19], 0, v[136:137]
	s_add_i32 m0, s17, 0xc000
	ds_read_b128 v[158:161], v141
	ds_read_b128 v[162:165], v141 offset:1024
	ds_read_b128 v[166:169], v141 offset:2048
	ds_read_b128 v[170:173], v141 offset:3072
	ds_read_b128 v[200:203], v141 offset:4096
	ds_read_b128 v[204:207], v141 offset:5120
	ds_read_b128 v[208:211], v141 offset:6144
	ds_read_b128 v[212:215], v141 offset:7168
	global_load_lds_dwordx4 v[174:175], off
	v_lshl_add_u64 v[174:175], s[18:19], 0, v[138:139]
	s_add_i32 m0, s17, 0xe000
	s_nop 0
	global_load_lds_dwordx4 v[174:175], off
	s_waitcnt lgkmcnt(8)
	s_barrier
	s_waitcnt lgkmcnt(0)
	v_mfma_f32_16x16x32_bf16 v[126:129], v[142:145], v[158:161], v[126:129]
	v_mfma_f32_16x16x32_bf16 v[118:121], v[150:153], v[158:161], v[118:121]
	v_mfma_f32_16x16x32_bf16 v[110:113], v[142:145], v[166:169], v[110:113]
	v_mfma_f32_16x16x32_bf16 v[102:105], v[150:153], v[166:169], v[102:105]
	v_mfma_f32_16x16x32_bf16 v[94:97], v[142:145], v[200:203], v[94:97]
	v_mfma_f32_16x16x32_bf16 v[86:89], v[150:153], v[200:203], v[86:89]
	v_mfma_f32_16x16x32_bf16 v[78:81], v[142:145], v[208:211], v[78:81]
	v_mfma_f32_16x16x32_bf16 v[70:73], v[150:153], v[208:211], v[70:73]
	v_mfma_f32_16x16x32_bf16 v[126:129], v[146:149], v[162:165], v[126:129]
	v_mfma_f32_16x16x32_bf16 v[118:121], v[154:157], v[162:165], v[118:121]
	v_mfma_f32_16x16x32_bf16 v[110:113], v[146:149], v[170:173], v[110:113]
	v_mfma_f32_16x16x32_bf16 v[102:105], v[154:157], v[170:173], v[102:105]
	v_mfma_f32_16x16x32_bf16 v[94:97], v[146:149], v[204:207], v[94:97]
	v_mfma_f32_16x16x32_bf16 v[86:89], v[154:157], v[204:207], v[86:89]
	v_mfma_f32_16x16x32_bf16 v[78:81], v[146:149], v[212:215], v[78:81]
	v_mfma_f32_16x16x32_bf16 v[70:73], v[154:157], v[212:215], v[70:73]
	s_barrier
	s_add_i32 s47, 0, 0x14000
	v_add_u32_e32 v174, s47, v131
	s_add_i32 s33, s33, s30
	ds_read_b128 v[216:219], v174
	ds_read_b128 v[220:223], v174 offset:1024
	ds_read_b128 v[224:227], v174 offset:2048
	ds_read_b128 v[228:231], v174 offset:3072
	v_lshl_add_u64 v[174:175], s[20:21], 0, v[134:135]
	s_mov_b32 m0, s33
	v_lshl_add_u64 v[182:183], s[20:21], 0, v[132:133]
	global_load_lds_dwordx4 v[174:175], off
	s_add_i32 m0, s33, 0x2000
	s_nop 0
	global_load_lds_dwordx4 v[182:183], off
	s_barrier
	s_waitcnt lgkmcnt(0)
	v_mfma_f32_16x16x32_bf16 v[122:125], v[216:219], v[158:161], v[122:125]
	v_mfma_f32_16x16x32_bf16 v[114:117], v[224:227], v[158:161], v[114:117]
	v_mfma_f32_16x16x32_bf16 v[106:109], v[216:219], v[166:169], v[106:109]
	v_mfma_f32_16x16x32_bf16 v[98:101], v[224:227], v[166:169], v[98:101]
	v_mfma_f32_16x16x32_bf16 v[90:93], v[216:219], v[200:203], v[90:93]
	v_mfma_f32_16x16x32_bf16 v[82:85], v[224:227], v[200:203], v[82:85]
	v_mfma_f32_16x16x32_bf16 v[74:77], v[216:219], v[208:211], v[74:77]
	v_mfma_f32_16x16x32_bf16 v[66:69], v[224:227], v[208:211], v[66:69]
	v_mfma_f32_16x16x32_bf16 v[122:125], v[220:223], v[162:165], v[122:125]
	v_mfma_f32_16x16x32_bf16 v[114:117], v[228:231], v[162:165], v[114:117]
	v_mfma_f32_16x16x32_bf16 v[106:109], v[220:223], v[170:173], v[106:109]
	v_mfma_f32_16x16x32_bf16 v[98:101], v[228:231], v[170:173], v[98:101]
	v_mfma_f32_16x16x32_bf16 v[90:93], v[220:223], v[204:207], v[90:93]
	v_mfma_f32_16x16x32_bf16 v[82:85], v[228:231], v[204:207], v[82:85]
	v_mfma_f32_16x16x32_bf16 v[74:77], v[220:223], v[212:215], v[74:77]
	v_mfma_f32_16x16x32_bf16 v[66:69], v[228:231], v[212:215], v[66:69]
	s_barrier
	s_mov_b32 m0, s17
	v_lshl_add_u64 v[184:185], s[22:23], 0, v[134:135]
	ds_read_b128 v[158:161], v141 offset:16384
	ds_read_b128 v[162:165], v141 offset:17408
	ds_read_b128 v[166:169], v141 offset:18432
	ds_read_b128 v[170:173], v141 offset:19456
	ds_read_b128 v[200:203], v141 offset:20480
	ds_read_b128 v[204:207], v141 offset:21504
	ds_read_b128 v[208:211], v141 offset:22528
	ds_read_b128 v[212:215], v141 offset:23552
	global_load_lds_dwordx4 v[184:185], off
	v_lshl_add_u64 v[232:233], s[22:23], 0, v[132:133]
	s_mov_b32 m0, s35
	s_nop 0
	global_load_lds_dwordx4 v[232:233], off
	s_barrier
	s_waitcnt lgkmcnt(0)
	v_mfma_f32_16x16x32_bf16 v[62:65], v[142:145], v[158:161], v[62:65]
	v_mfma_f32_16x16x32_bf16 v[54:57], v[150:153], v[158:161], v[54:57]
	v_mfma_f32_16x16x32_bf16 v[46:49], v[142:145], v[166:169], v[46:49]
	v_mfma_f32_16x16x32_bf16 v[38:41], v[150:153], v[166:169], v[38:41]
	v_mfma_f32_16x16x32_bf16 v[30:33], v[142:145], v[200:203], v[30:33]
	v_mfma_f32_16x16x32_bf16 v[22:25], v[150:153], v[200:203], v[22:25]
	v_mfma_f32_16x16x32_bf16 v[14:17], v[142:145], v[208:211], v[14:17]
	v_mfma_f32_16x16x32_bf16 v[6:9], v[150:153], v[208:211], v[6:9]
	v_mfma_f32_16x16x32_bf16 v[62:65], v[146:149], v[162:165], v[62:65]
	v_mfma_f32_16x16x32_bf16 v[54:57], v[154:157], v[162:165], v[54:57]
	v_mfma_f32_16x16x32_bf16 v[46:49], v[146:149], v[170:173], v[46:49]
	v_mfma_f32_16x16x32_bf16 v[38:41], v[154:157], v[170:173], v[38:41]
	v_mfma_f32_16x16x32_bf16 v[30:33], v[146:149], v[204:207], v[30:33]
	v_mfma_f32_16x16x32_bf16 v[22:25], v[154:157], v[204:207], v[22:25]
	v_mfma_f32_16x16x32_bf16 v[14:17], v[146:149], v[212:215], v[14:17]
	v_mfma_f32_16x16x32_bf16 v[6:9], v[154:157], v[212:215], v[6:9]
	s_barrier
; #define PG8_STAGE(bufoff, gbase, voff) do { _Pragma("unroll") for (int _i = 0; _i < 2; ++_i) \
;     __builtin_amdgcn_global_load_lds((const unsigned*)((const char*)(gbase) + (voff)[_i]), (PG8_LAS unsigned*)(lds + (bufoff) + ldsw + _i * 8192), 16, 0, 0); } while (0)
; #define PG8_LDA(dst, b, h) do { _Pragma("unroll") for (int m = 0; m < 4; ++m) _Pragma("unroll") for (int k = 0; k < 2; ++k) dst[m][k] = *(const PG8_LAS bf16x8*)(lds + PG8_SA(b, h) + aoff + m * 2048 + k * 1024); } while (0)
; #define PG8_LDB(dst, b, h) do { _Pragma("unroll") for (int n = 0; n < 2; ++n) _Pragma("unroll") for (int k = 0; k < 2; ++k) dst[n][k] = *(const PG8_LAS bf16x8*)(lds + PG8_SB(b, h) + boff + n * 2048 + k * 1024); } while (0)
; #define PG8_MMA(ai, bj, At, Bt) do { __builtin_amdgcn_s_setprio(1); _Pragma("unroll") for (int m = 0; m < 4; ++m) _Pragma("unroll") for (int n = 0; n < 2; ++n) _Pragma("unroll") for (int k = 0; k < 2; ++k) \
;     acc[ai][bj][m][n] = __builtin_amdgcn_mfma_f32_16x16x32_bf16(Bt[n][k], At[m][k], acc[ai][bj][m][n], 0, 0, 0); __builtin_amdgcn_s_setprio(0); } while (0)
; #define PG8_WAIT_V(n) asm volatile("s_waitcnt vmcnt(" #n ")" ::: "memory")
; #define PG8_WAIT_L(n) asm volatile("s_waitcnt lgkmcnt(" #n ")" ::: "memory")
; #define PG8_BAR __builtin_amdgcn_s_barrier()
; #define PG8_SCHED __builtin_amdgcn_sched_barrier(0)
; template <class Epi, class Sched>
; __device__ __forceinline__ void gemm_phase(PG8_LAS unsigned char* lds, const int lda, const int ldb, const Sched& S, const Epi& E) {
;     ...
;       PG8_STAGE(PG8_SB(0, 1), b2 + hstepB, voffB);
;       PG8_WAIT_V(6); PG8_BAR; PG8_MMA(1, 1, At, B1); PG8_BAR;
;       PG8_LDB(B0, 1, 0); PG8_SCHED; PG8_LDA(At, 1, 0); PG8_STAGE(PG8_SA(0, 1), a2 + hstepA, voffA);
;       PG8_WAIT_L(8); PG8_BAR; PG8_WAIT_L(0); PG8_MMA(0, 0, At, B0); PG8_BAR; PG8_SCHED;
;       PG8_LDB(B1, 1, 1); PG8_STAGE(PG8_SB(1, 0), b3, voffB);
;       PG8_BAR; PG8_WAIT_L(0); PG8_MMA(0, 1, At, B1); PG8_BAR;
;       PG8_LDA(At, 1, 1); PG8_STAGE(PG8_SA(1, 0), a3, voffA);
;       PG8_BAR; PG8_WAIT_L(0); PG8_MMA(1, 0, At, B0); PG8_BAR; PG8_SCHED;
	s_add_u32 s48, s20, 0x40000
	s_addc_u32 s49, s21, 0
	s_add_i32 s33, s47, s30
	v_lshl_add_u64 v[142:143], s[48:49], 0, v[134:135]
	s_mov_b32 m0, s33
	s_nop 0
	global_load_lds_dwordx4 v[142:143], off
	v_lshl_add_u64 v[142:143], s[48:49], 0, v[132:133]
	s_add_i32 m0, s33, 0x2000
	s_nop 0
	global_load_lds_dwordx4 v[142:143], off
	s_waitcnt vmcnt(6)
	s_barrier
	v_mfma_f32_16x16x32_bf16 v[58:61], v[216:219], v[158:161], v[58:61]
	v_mfma_f32_16x16x32_bf16 v[50:53], v[224:227], v[158:161], v[50:53]
	v_mfma_f32_16x16x32_bf16 v[42:45], v[216:219], v[166:169], v[42:45]
	v_mfma_f32_16x16x32_bf16 v[34:37], v[224:227], v[166:169], v[34:37]
	v_mfma_f32_16x16x32_bf16 v[26:29], v[216:219], v[200:203], v[26:29]
	v_mfma_f32_16x16x32_bf16 v[18:21], v[224:227], v[200:203], v[18:21]
	v_mfma_f32_16x16x32_bf16 v[10:13], v[216:219], v[208:211], v[10:13]
	v_mfma_f32_16x16x32_bf16 v[2:5], v[224:227], v[208:211], v[2:5]
	v_mfma_f32_16x16x32_bf16 v[58:61], v[220:223], v[162:165], v[58:61]
	v_mfma_f32_16x16x32_bf16 v[50:53], v[228:231], v[162:165], v[50:53]
	v_mfma_f32_16x16x32_bf16 v[42:45], v[220:223], v[170:173], v[42:45]
	v_mfma_f32_16x16x32_bf16 v[34:37], v[228:231], v[170:173], v[34:37]
	v_mfma_f32_16x16x32_bf16 v[26:29], v[220:223], v[204:207], v[26:29]
	v_mfma_f32_16x16x32_bf16 v[18:21], v[228:231], v[204:207], v[18:21]
	v_mfma_f32_16x16x32_bf16 v[10:13], v[220:223], v[212:215], v[10:13]
	v_mfma_f32_16x16x32_bf16 v[2:5], v[228:231], v[212:215], v[2:5]
	s_barrier
	s_add_i32 s33, 0, 0x18000
	v_add_u32_e32 v154, s33, v131
	ds_read_b128 v[142:145], v154
	ds_read_b128 v[146:149], v154 offset:1024
	ds_read_b128 v[150:153], v154 offset:2048
	ds_read_b128 v[154:157], v154 offset:3072
	s_add_u32 s22, s22, 0x40000
	s_addc_u32 s23, s23, 0
	s_mov_b32 m0, s36
	v_lshl_add_u64 v[216:217], s[22:23], 0, v[134:135]
	ds_read_b128 v[158:161], v141 offset:32768
	ds_read_b128 v[162:165], v141 offset:33792
	ds_read_b128 v[166:169], v141 offset:34816
	ds_read_b128 v[170:173], v141 offset:35840
	ds_read_b128 v[200:203], v141 offset:36864
	ds_read_b128 v[204:207], v141 offset:37888
	ds_read_b128 v[208:211], v141 offset:38912
	ds_read_b128 v[212:215], v141 offset:39936
	global_load_lds_dwordx4 v[216:217], off
	v_lshl_add_u64 v[216:217], s[22:23], 0, v[132:133]
	s_mov_b32 m0, s37
	s_nop 0
	global_load_lds_dwordx4 v[216:217], off
	s_waitcnt lgkmcnt(8)
	s_barrier
	s_waitcnt lgkmcnt(0)
	v_mfma_f32_16x16x32_bf16 v[126:129], v[142:145], v[158:161], v[126:129]
	v_mfma_f32_16x16x32_bf16 v[118:121], v[150:153], v[158:161], v[118:121]
	v_mfma_f32_16x16x32_bf16 v[110:113], v[142:145], v[166:169], v[110:113]
	v_mfma_f32_16x16x32_bf16 v[102:105], v[150:153], v[166:169], v[102:105]
	v_mfma_f32_16x16x32_bf16 v[94:97], v[142:145], v[200:203], v[94:97]
	v_mfma_f32_16x16x32_bf16 v[86:89], v[150:153], v[200:203], v[86:89]
	v_mfma_f32_16x16x32_bf16 v[78:81], v[142:145], v[208:211], v[78:81]
	v_mfma_f32_16x16x32_bf16 v[70:73], v[150:153], v[208:211], v[70:73]
	v_mfma_f32_16x16x32_bf16 v[126:129], v[146:149], v[162:165], v[126:129]
	v_mfma_f32_16x16x32_bf16 v[118:121], v[154:157], v[162:165], v[118:121]
	v_mfma_f32_16x16x32_bf16 v[110:113], v[146:149], v[170:173], v[110:113]
	v_mfma_f32_16x16x32_bf16 v[102:105], v[154:157], v[170:173], v[102:105]
	v_mfma_f32_16x16x32_bf16 v[94:97], v[146:149], v[204:207], v[94:97]
	v_mfma_f32_16x16x32_bf16 v[86:89], v[154:157], v[204:207], v[86:89]
	v_mfma_f32_16x16x32_bf16 v[78:81], v[146:149], v[212:215], v[78:81]
	v_mfma_f32_16x16x32_bf16 v[70:73], v[154:157], v[212:215], v[70:73]
	s_barrier
	s_add_i32 s22, 0, 0x1c000
	s_add_i32 s23, s33, s30
	v_add_u32_e32 v228, s22, v131
	v_lshl_add_u64 v[174:175], v[174:175], 0, s[86:87]
	s_mov_b32 m0, s23
	ds_read_b128 v[216:219], v228
	ds_read_b128 v[220:223], v228 offset:1024
	ds_read_b128 v[224:227], v228 offset:2048
	ds_read_b128 v[228:231], v228 offset:3072
	global_load_lds_dwordx4 v[174:175], off
	v_lshl_add_u64 v[174:175], v[182:183], 0, s[86:87]
	s_add_i32 m0, s23, 0x2000
	s_nop 0
	global_load_lds_dwordx4 v[174:175], off
	s_barrier
	s_waitcnt lgkmcnt(0)
	v_mfma_f32_16x16x32_bf16 v[122:125], v[216:219], v[158:161], v[122:125]
	v_mfma_f32_16x16x32_bf16 v[114:117], v[224:227], v[158:161], v[114:117]
	v_mfma_f32_16x16x32_bf16 v[106:109], v[216:219], v[166:169], v[106:109]
	v_mfma_f32_16x16x32_bf16 v[98:101], v[224:227], v[166:169], v[98:101]
	v_mfma_f32_16x16x32_bf16 v[90:93], v[216:219], v[200:203], v[90:93]
	v_mfma_f32_16x16x32_bf16 v[82:85], v[224:227], v[200:203], v[82:85]
	v_mfma_f32_16x16x32_bf16 v[74:77], v[216:219], v[208:211], v[74:77]
	v_mfma_f32_16x16x32_bf16 v[66:69], v[224:227], v[208:211], v[66:69]
	v_mfma_f32_16x16x32_bf16 v[122:125], v[220:223], v[162:165], v[122:125]
	v_mfma_f32_16x16x32_bf16 v[114:117], v[228:231], v[162:165], v[114:117]
	v_mfma_f32_16x16x32_bf16 v[106:109], v[220:223], v[170:173], v[106:109]
	v_mfma_f32_16x16x32_bf16 v[98:101], v[228:231], v[170:173], v[98:101]
	v_mfma_f32_16x16x32_bf16 v[90:93], v[220:223], v[204:207], v[90:93]
	v_mfma_f32_16x16x32_bf16 v[82:85], v[228:231], v[204:207], v[82:85]
	v_mfma_f32_16x16x32_bf16 v[74:77], v[220:223], v[212:215], v[74:77]
	v_mfma_f32_16x16x32_bf16 v[66:69], v[228:231], v[212:215], v[66:69]
	s_barrier
	s_mov_b32 m0, s38
	v_lshl_add_u64 v[174:175], v[184:185], 0, s[86:87]
	ds_read_b128 v[158:161], v141 offset:49152
	ds_read_b128 v[162:165], v141 offset:50176
	ds_read_b128 v[166:169], v141 offset:51200
	ds_read_b128 v[170:173], v141 offset:52224
	ds_read_b128 v[200:203], v141 offset:53248
	ds_read_b128 v[204:207], v141 offset:54272
	ds_read_b128 v[208:211], v141 offset:55296
	ds_read_b128 v[212:215], v141 offset:56320
	global_load_lds_dwordx4 v[174:175], off
	v_lshl_add_u64 v[174:175], v[232:233], 0, s[86:87]
	s_mov_b32 m0, s39
	s_nop 0
	global_load_lds_dwordx4 v[174:175], off
	s_barrier
; __device__ __forceinline__ float silu_f(float x) { return x * sigm(x); }
; #define PG8_STAGE(bufoff, gbase, voff) do { _Pragma("unroll") for (int _i = 0; _i < 2; ++_i) \
;     __builtin_amdgcn_global_load_lds((const unsigned*)((const char*)(gbase) + (voff)[_i]), (PG8_LAS unsigned*)(lds + (bufoff) + ldsw + _i * 8192), 16, 0, 0); } while (0)
; #define PG8_LDA(dst, b, h) do { _Pragma("unroll") for (int m = 0; m < 4; ++m) _Pragma("unroll") for (int k = 0; k < 2; ++k) dst[m][k] = *(const PG8_LAS bf16x8*)(lds + PG8_SA(b, h) + aoff + m * 2048 + k * 1024); } while (0)
; #define PG8_LDB(dst, b, h) do { _Pragma("unroll") for (int n = 0; n < 2; ++n) _Pragma("unroll") for (int k = 0; k < 2; ++k) dst[n][k] = *(const PG8_LAS bf16x8*)(lds + PG8_SB(b, h) + boff + n * 2048 + k * 1024); } while (0)
; #define PG8_WAIT_V(n) asm volatile("s_waitcnt vmcnt(" #n ")" ::: "memory")
; #define PG8_WAIT_L(n) asm volatile("s_waitcnt lgkmcnt(" #n ")" ::: "memory")
; template <class Epi, class Sched>
; __device__ __forceinline__ void gemm_phase(PG8_LAS unsigned char* lds, const int lda, const int ldb, const Sched& S, const Epi& E) {
;     ...
;       PG8_WAIT_L(8); PG8_BAR; PG8_WAIT_L(0); PG8_MMA(0, 0, At, B0); PG8_BAR; PG8_SCHED;
;       PG8_LDB(B1, 1, 1); PG8_STAGE(PG8_SB(1, 0), b3, voffB);
;       PG8_BAR; PG8_WAIT_L(0); PG8_MMA(0, 1, At, B1); PG8_BAR;
;       PG8_LDA(At, 1, 1); PG8_STAGE(PG8_SA(1, 0), a3, voffA);
;       PG8_BAR; PG8_WAIT_L(0); PG8_MMA(1, 0, At, B0); PG8_BAR; PG8_SCHED;
;       PG8_STAGE(PG8_SB(1, 1), b3 + hstepB, voffB);
;       PG8_WAIT_V(6); PG8_BAR; PG8_MMA(1, 1, At, B1); PG8_BAR;
;   __device__ __forceinline__ void operator()(const f32x4 (&acc)[2][2][4][2], const Unit& u, int wr, int wc, int fr, int fq) const {
; #pragma unroll
;     for (int ai = 0; ai < 2; ++ai)
; #pragma unroll
;       for (int m = 0; m < 4; ++m) {
;         const int r = u.pm * 256 + ai * 128 + wr * 64 + m * 16 + fr;
; #pragma unroll
;         for (int n = 0; n < 2; ++n) {
;           const f32x4 g = acc[ai][0][m][n], up = acc[ai][1][m][n];
;           const int c = u.pn * 128 + wc * 32 + n * 16 + 4 * fq;
;           uint2 w;
;           w.x = pack2(silu_f(g[0]) * up[0], silu_f(g[1]) * up[1]);
;           w.y = pack2(silu_f(g[2]) * up[2], silu_f(g[3]) * up[3]);
;           *reinterpret_cast<uint2*>(HID + (size_t)r * DFF + c) = w;
;         }
;       }
;   }
	s_waitcnt lgkmcnt(0)
	v_mfma_f32_16x16x32_bf16 v[62:65], v[142:145], v[158:161], v[62:65]
	v_mfma_f32_16x16x32_bf16 v[54:57], v[150:153], v[158:161], v[54:57]
	v_mfma_f32_16x16x32_bf16 v[46:49], v[142:145], v[166:169], v[46:49]
	v_mfma_f32_16x16x32_bf16 v[38:41], v[150:153], v[166:169], v[38:41]
	v_mfma_f32_16x16x32_bf16 v[30:33], v[142:145], v[200:203], v[30:33]
	v_mfma_f32_16x16x32_bf16 v[22:25], v[150:153], v[200:203], v[22:25]
	v_mfma_f32_16x16x32_bf16 v[14:17], v[142:145], v[208:211], v[14:17]
	v_mfma_f32_16x16x32_bf16 v[6:9], v[150:153], v[208:211], v[6:9]
	v_mfma_f32_16x16x32_bf16 v[62:65], v[146:149], v[162:165], v[62:65]
	v_mfma_f32_16x16x32_bf16 v[54:57], v[154:157], v[162:165], v[54:57]
	v_mfma_f32_16x16x32_bf16 v[46:49], v[146:149], v[170:173], v[46:49]
	v_mfma_f32_16x16x32_bf16 v[38:41], v[154:157], v[170:173], v[38:41]
	v_mfma_f32_16x16x32_bf16 v[30:33], v[146:149], v[204:207], v[30:33]
	v_mfma_f32_16x16x32_bf16 v[22:25], v[154:157], v[204:207], v[22:25]
	v_mfma_f32_16x16x32_bf16 v[14:17], v[146:149], v[212:215], v[14:17]
	v_mfma_f32_16x16x32_bf16 v[6:9], v[154:157], v[212:215], v[6:9]
	s_barrier
	s_add_u32 s20, s20, 0x40080
	s_addc_u32 s21, s21, 0
	s_add_i32 s22, s22, s30
	v_lshl_add_u64 v[142:143], s[20:21], 0, v[134:135]
	s_mov_b32 m0, s22
	s_nop 0
	global_load_lds_dwordx4 v[142:143], off
	v_lshl_add_u64 v[142:143], s[20:21], 0, v[132:133]
	s_add_i32 m0, s22, 0x2000
	s_nop 0
	global_load_lds_dwordx4 v[142:143], off
	s_waitcnt vmcnt(6)
	s_barrier
	v_mfma_f32_16x16x32_bf16 v[58:61], v[216:219], v[158:161], v[58:61]
	v_mfma_f32_16x16x32_bf16 v[50:53], v[224:227], v[158:161], v[50:53]
	v_mfma_f32_16x16x32_bf16 v[42:45], v[216:219], v[166:169], v[42:45]
	v_mfma_f32_16x16x32_bf16 v[34:37], v[224:227], v[166:169], v[34:37]
	v_mfma_f32_16x16x32_bf16 v[26:29], v[216:219], v[200:203], v[26:29]
	v_mfma_f32_16x16x32_bf16 v[18:21], v[224:227], v[200:203], v[18:21]
	v_mfma_f32_16x16x32_bf16 v[10:13], v[216:219], v[208:211], v[10:13]
	v_mfma_f32_16x16x32_bf16 v[2:5], v[224:227], v[208:211], v[2:5]
	v_mfma_f32_16x16x32_bf16 v[58:61], v[220:223], v[162:165], v[58:61]
	v_mfma_f32_16x16x32_bf16 v[50:53], v[228:231], v[162:165], v[50:53]
	v_mfma_f32_16x16x32_bf16 v[42:45], v[220:223], v[170:173], v[42:45]
	v_mfma_f32_16x16x32_bf16 v[34:37], v[228:231], v[170:173], v[34:37]
	v_mfma_f32_16x16x32_bf16 v[26:29], v[220:223], v[204:207], v[26:29]
	v_mfma_f32_16x16x32_bf16 v[18:21], v[228:231], v[204:207], v[18:21]
	v_mfma_f32_16x16x32_bf16 v[10:13], v[220:223], v[212:215], v[10:13]
	v_mfma_f32_16x16x32_bf16 v[2:5], v[228:231], v[212:215], v[2:5]
	s_add_i32 s46, s46, 2
	s_add_u32 s18, s18, 0x100
	s_addc_u32 s19, s19, 0
	s_add_u32 s44, s44, 0x100
	s_addc_u32 s45, s45, 0
	s_cmp_gt_u32 s46, 13
	s_barrier
	s_cbranch_scc0 .LBB0_1604
	v_lshl_or_b32 v144, s41, 7, v140
	v_lshl_add_u32 v142, s16, 8, v1
	s_and_b64 vcc, exec, s[6:7]
	s_mov_b32 s41, s0
	s_mov_b32 s16, s10
	s_mov_b64 s[20:21], s[14:15]
	s_mov_b32 s100, 0xbfb8aa3b
	v_bfe_u32 v143, v176, 4, 1
	v_mul_u32_u24_e32 v143, 24, v143
	v_lshl_add_u32 v146, v144, 1, v143
	v_mad_u32_u24 v146, v142, s50, v146
	v_pk_mul_f32 v[150:151], v[126:127], s[100:101] op_sel_hi:[1,0]
	v_pk_mul_f32 v[152:153], v[128:129], s[100:101] op_sel_hi:[1,0]
	v_pk_mul_f32 v[154:155], v[118:119], s[100:101] op_sel_hi:[1,0]
	v_pk_mul_f32 v[156:157], v[120:121], s[100:101] op_sel_hi:[1,0]
	v_exp_f32_e32 v150, v150
	v_exp_f32_e32 v151, v151
	v_exp_f32_e32 v152, v152
	v_exp_f32_e32 v153, v153
	v_exp_f32_e32 v154, v154
	v_exp_f32_e32 v155, v155
	v_exp_f32_e32 v156, v156
	v_exp_f32_e32 v157, v157
	v_pk_add_f32 v[150:151], v[150:151], 1.0 op_sel_hi:[1,0]
	v_pk_add_f32 v[152:153], v[152:153], 1.0 op_sel_hi:[1,0]
	v_pk_add_f32 v[154:155], v[154:155], 1.0 op_sel_hi:[1,0]
	v_pk_add_f32 v[156:157], v[156:157], 1.0 op_sel_hi:[1,0]
	v_rcp_f32_e32 v158, v150
	v_rcp_f32_e32 v159, v151
	v_rcp_f32_e32 v160, v152
	v_rcp_f32_e32 v161, v153
	v_rcp_f32_e32 v162, v154
	v_rcp_f32_e32 v163, v155
	v_rcp_f32_e32 v164, v156
	v_rcp_f32_e32 v165, v157
	v_mov_b32_e32 v208, v146
	v_pk_mul_f32 v[166:167], v[126:127], v[158:159]
	v_pk_mul_f32 v[168:169], v[128:129], v[160:161]
	v_pk_mul_f32 v[170:171], v[118:119], v[162:163]
	v_pk_mul_f32 v[172:173], v[120:121], v[164:165]
	v_pk_mul_f32 v[166:167], v[166:167], v[122:123]
	v_pk_mul_f32 v[168:169], v[168:169], v[124:125]
	v_pk_mul_f32 v[170:171], v[170:171], v[114:115]
	v_pk_mul_f32 v[172:173], v[172:173], v[116:117]
	v_cvt_pk_bf16_f32 v200, v166, v167
	v_cvt_pk_bf16_f32 v201, v168, v169
	v_cvt_pk_bf16_f32 v202, v170, v171
	v_cvt_pk_bf16_f32 v203, v172, v173
	s_nop 1
	v_permlane16_swap_b32_e32 v200, v202
	v_permlane16_swap_b32_e32 v201, v203
	global_store_dwordx4 v208, v[200:203], s[84:85]
	v_pk_mul_f32 v[150:151], v[110:111], s[100:101] op_sel_hi:[1,0]
	v_pk_mul_f32 v[152:153], v[112:113], s[100:101] op_sel_hi:[1,0]
	v_pk_mul_f32 v[154:155], v[102:103], s[100:101] op_sel_hi:[1,0]
	v_pk_mul_f32 v[156:157], v[104:105], s[100:101] op_sel_hi:[1,0]
	v_exp_f32_e32 v150, v150
	v_exp_f32_e32 v151, v151
	v_exp_f32_e32 v152, v152
	v_exp_f32_e32 v153, v153
	v_exp_f32_e32 v154, v154
	v_exp_f32_e32 v155, v155
	v_exp_f32_e32 v156, v156
	v_exp_f32_e32 v157, v157
	v_pk_add_f32 v[150:151], v[150:151], 1.0 op_sel_hi:[1,0]
	v_pk_add_f32 v[152:153], v[152:153], 1.0 op_sel_hi:[1,0]
	v_pk_add_f32 v[154:155], v[154:155], 1.0 op_sel_hi:[1,0]
	v_pk_add_f32 v[156:157], v[156:157], 1.0 op_sel_hi:[1,0]
	v_rcp_f32_e32 v158, v150
	v_rcp_f32_e32 v159, v151
	v_rcp_f32_e32 v160, v152
	v_rcp_f32_e32 v161, v153
	v_rcp_f32_e32 v162, v154
	v_rcp_f32_e32 v163, v155
	v_rcp_f32_e32 v164, v156
	v_rcp_f32_e32 v165, v157
	s_mul_i32 s101, s50, 0x10
; __device__ __forceinline__ float silu_f(float x) { return x * sigm(x); }
;   __device__ __forceinline__ void operator()(const f32x4 (&acc)[2][2][4][2], const Unit& u, int wr, int wc, int fr, int fq) const {
; #pragma unroll
;     for (int ai = 0; ai < 2; ++ai)
; #pragma unroll
;       for (int m = 0; m < 4; ++m) {
;         const int r = u.pm * 256 + ai * 128 + wr * 64 + m * 16 + fr;
; #pragma unroll
;         for (int n = 0; n < 2; ++n) {
;           const f32x4 g = acc[ai][0][m][n], up = acc[ai][1][m][n];
;           const int c = u.pn * 128 + wc * 32 + n * 16 + 4 * fq;
;           uint2 w;
;           w.x = pack2(silu_f(g[0]) * up[0], silu_f(g[1]) * up[1]);
;           w.y = pack2(silu_f(g[2]) * up[2], silu_f(g[3]) * up[3]);
;           *reinterpret_cast<uint2*>(HID + (size_t)r * DFF + c) = w;
;         }
;       }
;   }
	v_add_u32_e32 v210, s101, v146
	v_pk_mul_f32 v[166:167], v[110:111], v[158:159]
	v_pk_mul_f32 v[168:169], v[112:113], v[160:161]
	v_pk_mul_f32 v[170:171], v[102:103], v[162:163]
	v_pk_mul_f32 v[172:173], v[104:105], v[164:165]
	v_pk_mul_f32 v[166:167], v[166:167], v[106:107]
	v_pk_mul_f32 v[168:169], v[168:169], v[108:109]
	v_pk_mul_f32 v[170:171], v[170:171], v[98:99]
	v_pk_mul_f32 v[172:173], v[172:173], v[100:101]
	v_cvt_pk_bf16_f32 v204, v166, v167
	v_cvt_pk_bf16_f32 v205, v168, v169
	v_cvt_pk_bf16_f32 v206, v170, v171
	v_cvt_pk_bf16_f32 v207, v172, v173
	s_nop 1
	v_permlane16_swap_b32_e32 v204, v206
	v_permlane16_swap_b32_e32 v205, v207
	global_store_dwordx4 v210, v[204:207], s[84:85]
	v_pk_mul_f32 v[150:151], v[94:95], s[100:101] op_sel_hi:[1,0]
	v_pk_mul_f32 v[152:153], v[96:97], s[100:101] op_sel_hi:[1,0]
	v_pk_mul_f32 v[154:155], v[86:87], s[100:101] op_sel_hi:[1,0]
	v_pk_mul_f32 v[156:157], v[88:89], s[100:101] op_sel_hi:[1,0]
	v_exp_f32_e32 v150, v150
	v_exp_f32_e32 v151, v151
	v_exp_f32_e32 v152, v152
	v_exp_f32_e32 v153, v153
	v_exp_f32_e32 v154, v154
	v_exp_f32_e32 v155, v155
	v_exp_f32_e32 v156, v156
	v_exp_f32_e32 v157, v157
	v_pk_add_f32 v[150:151], v[150:151], 1.0 op_sel_hi:[1,0]
	v_pk_add_f32 v[152:153], v[152:153], 1.0 op_sel_hi:[1,0]
	v_pk_add_f32 v[154:155], v[154:155], 1.0 op_sel_hi:[1,0]
	v_pk_add_f32 v[156:157], v[156:157], 1.0 op_sel_hi:[1,0]
	v_rcp_f32_e32 v158, v150
	v_rcp_f32_e32 v159, v151
	v_rcp_f32_e32 v160, v152
	v_rcp_f32_e32 v161, v153
	v_rcp_f32_e32 v162, v154
	v_rcp_f32_e32 v163, v155
	v_rcp_f32_e32 v164, v156
	v_rcp_f32_e32 v165, v157
	s_mul_i32 s101, s50, 0x20
	v_add_u32_e32 v208, s101, v146
	v_pk_mul_f32 v[166:167], v[94:95], v[158:159]
	v_pk_mul_f32 v[168:169], v[96:97], v[160:161]
	v_pk_mul_f32 v[170:171], v[86:87], v[162:163]
	v_pk_mul_f32 v[172:173], v[88:89], v[164:165]
	v_pk_mul_f32 v[166:167], v[166:167], v[90:91]
	v_pk_mul_f32 v[168:169], v[168:169], v[92:93]
	v_pk_mul_f32 v[170:171], v[170:171], v[82:83]
	v_pk_mul_f32 v[172:173], v[172:173], v[84:85]
	v_cvt_pk_bf16_f32 v200, v166, v167
	v_cvt_pk_bf16_f32 v201, v168, v169
	v_cvt_pk_bf16_f32 v202, v170, v171
	v_cvt_pk_bf16_f32 v203, v172, v173
	s_nop 1
	v_permlane16_swap_b32_e32 v200, v202
	v_permlane16_swap_b32_e32 v201, v203
	global_store_dwordx4 v208, v[200:203], s[84:85]
	v_pk_mul_f32 v[150:151], v[78:79], s[100:101] op_sel_hi:[1,0]
	v_pk_mul_f32 v[152:153], v[80:81], s[100:101] op_sel_hi:[1,0]
	v_pk_mul_f32 v[154:155], v[70:71], s[100:101] op_sel_hi:[1,0]
	v_pk_mul_f32 v[156:157], v[72:73], s[100:101] op_sel_hi:[1,0]
	v_exp_f32_e32 v150, v150
	v_exp_f32_e32 v151, v151
	v_exp_f32_e32 v152, v152
	v_exp_f32_e32 v153, v153
	v_exp_f32_e32 v154, v154
	v_exp_f32_e32 v155, v155
	v_exp_f32_e32 v156, v156
	v_exp_f32_e32 v157, v157
	v_pk_add_f32 v[150:151], v[150:151], 1.0 op_sel_hi:[1,0]
	v_pk_add_f32 v[152:153], v[152:153], 1.0 op_sel_hi:[1,0]
	v_pk_add_f32 v[154:155], v[154:155], 1.0 op_sel_hi:[1,0]
	v_pk_add_f32 v[156:157], v[156:157], 1.0 op_sel_hi:[1,0]
	v_rcp_f32_e32 v158, v150
	v_rcp_f32_e32 v159, v151
	v_rcp_f32_e32 v160, v152
	v_rcp_f32_e32 v161, v153
	v_rcp_f32_e32 v162, v154
	v_rcp_f32_e32 v163, v155
	v_rcp_f32_e32 v164, v156
	v_rcp_f32_e32 v165, v157
	s_mul_i32 s101, s50, 0x30
	v_add_u32_e32 v210, s101, v146
	v_pk_mul_f32 v[166:167], v[78:79], v[158:159]
	v_pk_mul_f32 v[168:169], v[80:81], v[160:161]
	v_pk_mul_f32 v[170:171], v[70:71], v[162:163]
	v_pk_mul_f32 v[172:173], v[72:73], v[164:165]
	v_pk_mul_f32 v[166:167], v[166:167], v[74:75]
	v_pk_mul_f32 v[168:169], v[168:169], v[76:77]
	v_pk_mul_f32 v[170:171], v[170:171], v[66:67]
	v_pk_mul_f32 v[172:173], v[172:173], v[68:69]
	v_cvt_pk_bf16_f32 v204, v166, v167
	v_cvt_pk_bf16_f32 v205, v168, v169
	v_cvt_pk_bf16_f32 v206, v170, v171
	v_cvt_pk_bf16_f32 v207, v172, v173
	s_nop 1
	v_permlane16_swap_b32_e32 v204, v206
	v_permlane16_swap_b32_e32 v205, v207
	global_store_dwordx4 v210, v[204:207], s[84:85]
	v_pk_mul_f32 v[150:151], v[62:63], s[100:101] op_sel_hi:[1,0]
	v_pk_mul_f32 v[152:153], v[64:65], s[100:101] op_sel_hi:[1,0]
	v_pk_mul_f32 v[154:155], v[54:55], s[100:101] op_sel_hi:[1,0]
	v_pk_mul_f32 v[156:157], v[56:57], s[100:101] op_sel_hi:[1,0]
	v_exp_f32_e32 v150, v150
	v_exp_f32_e32 v151, v151
	v_exp_f32_e32 v152, v152
	v_exp_f32_e32 v153, v153
	v_exp_f32_e32 v154, v154
	v_exp_f32_e32 v155, v155
	v_exp_f32_e32 v156, v156
	v_exp_f32_e32 v157, v157
	v_pk_add_f32 v[150:151], v[150:151], 1.0 op_sel_hi:[1,0]
	v_pk_add_f32 v[152:153], v[152:153], 1.0 op_sel_hi:[1,0]
	v_pk_add_f32 v[154:155], v[154:155], 1.0 op_sel_hi:[1,0]
	v_pk_add_f32 v[156:157], v[156:157], 1.0 op_sel_hi:[1,0]
	v_rcp_f32_e32 v158, v150
	v_rcp_f32_e32 v159, v151
	v_rcp_f32_e32 v160, v152
	v_rcp_f32_e32 v161, v153
	v_rcp_f32_e32 v162, v154
	v_rcp_f32_e32 v163, v155
	v_rcp_f32_e32 v164, v156
	v_rcp_f32_e32 v165, v157
	s_mul_i32 s101, s50, 0x80
	v_add_u32_e32 v208, s101, v146
	v_pk_mul_f32 v[166:167], v[62:63], v[158:159]
	v_pk_mul_f32 v[168:169], v[64:65], v[160:161]
	v_pk_mul_f32 v[170:171], v[54:55], v[162:163]
	v_pk_mul_f32 v[172:173], v[56:57], v[164:165]
	v_pk_mul_f32 v[166:167], v[166:167], v[58:59]
	v_pk_mul_f32 v[168:169], v[168:169], v[60:61]
	v_pk_mul_f32 v[170:171], v[170:171], v[50:51]
	v_pk_mul_f32 v[172:173], v[172:173], v[52:53]
	v_cvt_pk_bf16_f32 v200, v166, v167
	v_cvt_pk_bf16_f32 v201, v168, v169
	v_cvt_pk_bf16_f32 v202, v170, v171
	v_cvt_pk_bf16_f32 v203, v172, v173
	s_nop 1
	v_permlane16_swap_b32_e32 v200, v202
	v_permlane16_swap_b32_e32 v201, v203
	global_store_dwordx4 v208, v[200:203], s[84:85]
; __device__ __forceinline__ float silu_f(float x) { return x * sigm(x); }
; #define PG8_WAIT_V(n) asm volatile("s_waitcnt vmcnt(" #n ")" ::: "memory")
; #define PG8_BAR __builtin_amdgcn_s_barrier()
;   __device__ __forceinline__ int kt(const Unit& u) const { return ((u.pn & 7) < 4) ? 4 : 16; }
; template <class Epi, class Sched>
; __device__ __forceinline__ void gemm_phase(PG8_LAS unsigned char* lds, const int lda, const int ldb, const Sched& S, const Epi& E) {
;     ...
;     cur = nxt; cA = nA; cB = nB; ++ui;
;     nt = S.kt(cur);
;   }
;   PG8_WAIT_V(0);
;   if (wr == 0) PG8_BAR;
;   PG8_BAR;
;   __device__ __forceinline__ void operator()(const f32x4 (&acc)[2][2][4][2], const Unit& u, int wr, int wc, int fr, int fq) const {
; #pragma unroll
;     for (int ai = 0; ai < 2; ++ai)
; #pragma unroll
;       for (int m = 0; m < 4; ++m) {
;         const int r = u.pm * 256 + ai * 128 + wr * 64 + m * 16 + fr;
; #pragma unroll
;         for (int n = 0; n < 2; ++n) {
;           const f32x4 g = acc[ai][0][m][n], up = acc[ai][1][m][n];
;           const int c = u.pn * 128 + wc * 32 + n * 16 + 4 * fq;
;           uint2 w;
;           w.x = pack2(silu_f(g[0]) * up[0], silu_f(g[1]) * up[1]);
;           w.y = pack2(silu_f(g[2]) * up[2], silu_f(g[3]) * up[3]);
;           *reinterpret_cast<uint2*>(HID + (size_t)r * DFF + c) = w;
;         }
;       }
;   }
	v_pk_mul_f32 v[150:151], v[46:47], s[100:101] op_sel_hi:[1,0]
	v_pk_mul_f32 v[152:153], v[48:49], s[100:101] op_sel_hi:[1,0]
	v_pk_mul_f32 v[154:155], v[38:39], s[100:101] op_sel_hi:[1,0]
	v_pk_mul_f32 v[156:157], v[40:41], s[100:101] op_sel_hi:[1,0]
	v_exp_f32_e32 v150, v150
	v_exp_f32_e32 v151, v151
	v_exp_f32_e32 v152, v152
	v_exp_f32_e32 v153, v153
	v_exp_f32_e32 v154, v154
	v_exp_f32_e32 v155, v155
	v_exp_f32_e32 v156, v156
	v_exp_f32_e32 v157, v157
	v_pk_add_f32 v[150:151], v[150:151], 1.0 op_sel_hi:[1,0]
	v_pk_add_f32 v[152:153], v[152:153], 1.0 op_sel_hi:[1,0]
	v_pk_add_f32 v[154:155], v[154:155], 1.0 op_sel_hi:[1,0]
	v_pk_add_f32 v[156:157], v[156:157], 1.0 op_sel_hi:[1,0]
	v_rcp_f32_e32 v158, v150
	v_rcp_f32_e32 v159, v151
	v_rcp_f32_e32 v160, v152
	v_rcp_f32_e32 v161, v153
	v_rcp_f32_e32 v162, v154
	v_rcp_f32_e32 v163, v155
	v_rcp_f32_e32 v164, v156
	v_rcp_f32_e32 v165, v157
	s_mul_i32 s101, s50, 0x90
	v_add_u32_e32 v210, s101, v146
	v_pk_mul_f32 v[166:167], v[46:47], v[158:159]
	v_pk_mul_f32 v[168:169], v[48:49], v[160:161]
	v_pk_mul_f32 v[170:171], v[38:39], v[162:163]
	v_pk_mul_f32 v[172:173], v[40:41], v[164:165]
	v_pk_mul_f32 v[166:167], v[166:167], v[42:43]
	v_pk_mul_f32 v[168:169], v[168:169], v[44:45]
	v_pk_mul_f32 v[170:171], v[170:171], v[34:35]
	v_pk_mul_f32 v[172:173], v[172:173], v[36:37]
	v_cvt_pk_bf16_f32 v204, v166, v167
	v_cvt_pk_bf16_f32 v205, v168, v169
	v_cvt_pk_bf16_f32 v206, v170, v171
	v_cvt_pk_bf16_f32 v207, v172, v173
	s_nop 1
	v_permlane16_swap_b32_e32 v204, v206
	v_permlane16_swap_b32_e32 v205, v207
	global_store_dwordx4 v210, v[204:207], s[84:85]
	v_pk_mul_f32 v[150:151], v[30:31], s[100:101] op_sel_hi:[1,0]
	v_pk_mul_f32 v[152:153], v[32:33], s[100:101] op_sel_hi:[1,0]
	v_pk_mul_f32 v[154:155], v[22:23], s[100:101] op_sel_hi:[1,0]
	v_pk_mul_f32 v[156:157], v[24:25], s[100:101] op_sel_hi:[1,0]
	v_exp_f32_e32 v150, v150
	v_exp_f32_e32 v151, v151
	v_exp_f32_e32 v152, v152
	v_exp_f32_e32 v153, v153
	v_exp_f32_e32 v154, v154
	v_exp_f32_e32 v155, v155
	v_exp_f32_e32 v156, v156
	v_exp_f32_e32 v157, v157
	v_pk_add_f32 v[150:151], v[150:151], 1.0 op_sel_hi:[1,0]
	v_pk_add_f32 v[152:153], v[152:153], 1.0 op_sel_hi:[1,0]
	v_pk_add_f32 v[154:155], v[154:155], 1.0 op_sel_hi:[1,0]
	v_pk_add_f32 v[156:157], v[156:157], 1.0 op_sel_hi:[1,0]
	v_rcp_f32_e32 v158, v150
	v_rcp_f32_e32 v159, v151
	v_rcp_f32_e32 v160, v152
	v_rcp_f32_e32 v161, v153
	v_rcp_f32_e32 v162, v154
	v_rcp_f32_e32 v163, v155
	v_rcp_f32_e32 v164, v156
	v_rcp_f32_e32 v165, v157
	s_mul_i32 s101, s50, 0xa0
	v_add_u32_e32 v208, s101, v146
	v_pk_mul_f32 v[166:167], v[30:31], v[158:159]
	v_pk_mul_f32 v[168:169], v[32:33], v[160:161]
	v_pk_mul_f32 v[170:171], v[22:23], v[162:163]
	v_pk_mul_f32 v[172:173], v[24:25], v[164:165]
	v_pk_mul_f32 v[166:167], v[166:167], v[26:27]
	v_pk_mul_f32 v[168:169], v[168:169], v[28:29]
	v_pk_mul_f32 v[170:171], v[170:171], v[18:19]
	v_pk_mul_f32 v[172:173], v[172:173], v[20:21]
	v_cvt_pk_bf16_f32 v200, v166, v167
	v_cvt_pk_bf16_f32 v201, v168, v169
	v_cvt_pk_bf16_f32 v202, v170, v171
	v_cvt_pk_bf16_f32 v203, v172, v173
	s_nop 1
	v_permlane16_swap_b32_e32 v200, v202
	v_permlane16_swap_b32_e32 v201, v203
	global_store_dwordx4 v208, v[200:203], s[84:85]
	v_pk_mul_f32 v[150:151], v[14:15], s[100:101] op_sel_hi:[1,0]
	v_pk_mul_f32 v[152:153], v[16:17], s[100:101] op_sel_hi:[1,0]
	v_pk_mul_f32 v[154:155], v[6:7], s[100:101] op_sel_hi:[1,0]
	v_pk_mul_f32 v[156:157], v[8:9], s[100:101] op_sel_hi:[1,0]
	v_exp_f32_e32 v150, v150
	v_exp_f32_e32 v151, v151
	v_exp_f32_e32 v152, v152
	v_exp_f32_e32 v153, v153
	v_exp_f32_e32 v154, v154
	v_exp_f32_e32 v155, v155
	v_exp_f32_e32 v156, v156
	v_exp_f32_e32 v157, v157
	v_pk_add_f32 v[150:151], v[150:151], 1.0 op_sel_hi:[1,0]
	v_pk_add_f32 v[152:153], v[152:153], 1.0 op_sel_hi:[1,0]
	v_pk_add_f32 v[154:155], v[154:155], 1.0 op_sel_hi:[1,0]
	v_pk_add_f32 v[156:157], v[156:157], 1.0 op_sel_hi:[1,0]
	v_rcp_f32_e32 v158, v150
	v_rcp_f32_e32 v159, v151
	v_rcp_f32_e32 v160, v152
	v_rcp_f32_e32 v161, v153
	v_rcp_f32_e32 v162, v154
	v_rcp_f32_e32 v163, v155
	v_rcp_f32_e32 v164, v156
	v_rcp_f32_e32 v165, v157
	s_mul_i32 s101, s50, 0xb0
	v_add_u32_e32 v210, s101, v146
	v_pk_mul_f32 v[166:167], v[14:15], v[158:159]
	v_pk_mul_f32 v[168:169], v[16:17], v[160:161]
	v_pk_mul_f32 v[170:171], v[6:7], v[162:163]
	v_pk_mul_f32 v[172:173], v[8:9], v[164:165]
	v_pk_mul_f32 v[166:167], v[166:167], v[10:11]
	v_pk_mul_f32 v[168:169], v[168:169], v[12:13]
	v_pk_mul_f32 v[170:171], v[170:171], v[2:3]
	v_pk_mul_f32 v[172:173], v[172:173], v[4:5]
	v_cvt_pk_bf16_f32 v204, v166, v167
	v_cvt_pk_bf16_f32 v205, v168, v169
	v_cvt_pk_bf16_f32 v206, v170, v171
	v_cvt_pk_bf16_f32 v207, v172, v173
	s_nop 1
	v_permlane16_swap_b32_e32 v204, v206
	v_permlane16_swap_b32_e32 v205, v207
	global_store_dwordx4 v210, v[204:207], s[84:85]
	s_mov_b64 s[18:19], s[12:13]
	s_cbranch_vccz .LBB0_1601
	s_waitcnt vmcnt(0)
	v_readlane_b32 s40, v253, 12
	s_cmpk_gt_u32 s9, 0xff
	v_readlane_b32 s41, v253, 13
	v_readlane_b32 s44, v253, 16
	v_readlane_b32 s45, v253, 17
	v_readlane_b32 s52, v253, 24
	v_readlane_b32 s53, v253, 25
	v_readlane_b32 s54, v253, 26
	v_readlane_b32 s55, v253, 27
	v_readlane_b32 s38, v255, 23
	v_readlane_b32 s42, v253, 14
	v_readlane_b32 s43, v253, 15
	v_readlane_b32 s46, v253, 18
	v_readlane_b32 s47, v253, 19
	v_readlane_b32 s48, v253, 20
	v_readlane_b32 s49, v253, 21
	v_readlane_b32 s50, v253, 22
	v_readlane_b32 s51, v253, 23
	v_readlane_b32 s39, v255, 24
	s_cbranch_scc1 .LBB0_1608
	s_barrier
